# SSM scans: bu now from 32x32x16 block-sparse MFMAs (4 per 16-token tile instead of 16), 2 LDS operand reads per tile
# speedup vs baseline: 1.0266x; 1.0031x over previous
; template <int PASS> __device__ void ssm_pass(const Params& P, int l, LAS unsigned char* lds) {
;     ...
;     for (int unit = blockIdx.x; unit < 256; unit += G) {
;         const int b = unit >> 4, r = (unit >> 2) & 3, g = (unit & 3) * 8 + wave;
;         const size_t tok0 = (size_t)b * SEQ + r * 1024;
;         const f32x2 a = *(const f32x2*)(lamb + (g * 64 + lane) * 2);
;         bf16x4 bf[8];
; #pragma unroll
;         for (int t = 0; t < 8; ++t) bf[t] = *(const bf16x4*)(Bfrag + ((size_t)(g * 8 + t) * 64 + lane) * 4);
;         float sr = 0.f, si = 0.f;
;         bf16x8 cf[4]; f32x4 dd;
;         if (PASS == 2) {
;             const f32x2 a1k = *(const f32x2*)(lamb1k + (g * 64 + lane) * 2);
;             for (int rr = 0; rr < r; ++rr) { const f32x2 e = *(const f32x2*)(E + ((size_t)((b * 32 + g) * 4 + rr) * 64 + lane) * 2);
;                 const float nr = a1k.x * sr - a1k.y * si + e.x, ni = a1k.x * si + a1k.y * sr + e.y; sr = nr; si = ni; }
; #pragma unroll
;             for (int kt = 0; kt < 4; ++kt) cf[kt] = *(const bf16x8*)(Cfrag + ((size_t)(g * 4 + kt) * 64 + lane) * 8);
;             dd = *(const f32x4*)(dskip + g * 16 + 4 * fq);
.LBB0_324:
	s_lshl_b32 s12, s24, 3
	s_and_b32 s25, s12, 24
	s_add_i32 s25, s25, s20
	s_lshl_b32 s12, s25, 3
	s_ashr_i32 s13, s12, 31
	s_lshl_b64 s[16:17], s[12:13], 9
	v_lshl_add_u64 v[4:5], v[24:25], 0, s[16:17]
	s_or_b32 s16, s12, 1
	s_ashr_i32 s17, s16, 31
	s_lshl_b64 s[16:17], s[16:17], 9
	v_lshl_add_u64 v[6:7], v[24:25], 0, s[16:17]
	s_or_b32 s16, s12, 2
	s_ashr_i32 s17, s16, 31
	s_lshl_b64 s[16:17], s[16:17], 9
	v_lshl_or_b32 v0, s25, 7, v66
	v_lshl_add_u64 v[8:9], v[24:25], 0, s[16:17]
	s_or_b32 s16, s12, 3
	v_ashrrev_i32_e32 v1, 31, v0
	s_ashr_i32 s17, s16, 31
	v_lshl_add_u64 v[2:3], v[0:1], 2, s[0:1]
	s_lshl_b64 s[16:17], s[16:17], 9
	global_load_dwordx2 v[36:37], v[2:3], off
	v_and_b32_e32 v72, 16, v162
	v_mul_u32_u24_e32 v72, 24, v72
	v_mov_b32_e32 v73, 0
	v_lshl_add_u64 v[70:71], v[4:5], 0, v[72:73]
	global_load_dwordx2 v[38:39], v[70:71], off
	global_load_dwordx2 v[40:41], v[70:71], off offset:128
	global_load_dwordx2 v[42:43], v[70:71], off offset:1024
	global_load_dwordx2 v[44:45], v[70:71], off offset:1152
	global_load_dwordx2 v[46:47], v[70:71], off offset:2048
	global_load_dwordx2 v[48:49], v[70:71], off offset:2176
	global_load_dwordx2 v[50:51], v[70:71], off offset:3072
	global_load_dwordx2 v[52:53], v[70:71], off offset:3200
	v_lshl_add_u64 v[2:3], v[24:25], 0, s[16:17]
	s_or_b32 s16, s12, 4
	s_ashr_i32 s17, s16, 31
	s_lshl_b64 s[16:17], s[16:17], 9
	v_lshl_add_u64 v[4:5], v[24:25], 0, s[16:17]
	s_or_b32 s16, s12, 5
	s_ashr_i32 s17, s16, 31
	s_lshl_b64 s[16:17], s[16:17], 9
	v_lshl_add_u64 v[6:7], v[24:25], 0, s[16:17]
	s_or_b32 s16, s12, 6
	s_ashr_i32 s17, s16, 31
	s_or_b32 s12, s12, 7
	s_lshl_b64 s[16:17], s[16:17], 9
	s_ashr_i32 s13, s12, 31
	v_lshl_add_u64 v[8:9], v[24:25], 0, s[16:17]
	s_lshl_b64 s[12:13], s[12:13], 9
	v_lshl_add_u64 v[2:3], v[24:25], 0, s[12:13]
	s_lshr_b32 s28, s24, 2
	s_bfe_u32 s13, s24, 0x20002
	s_ashr_i32 s16, s24, 4
	s_cmp_lg_u32 s13, 0
	v_bfe_u32 v56, v23, 3, 2
	s_cbranch_scc0 .LBB0_333
	v_lshl_add_u64 v[0:1], v[0:1], 2, s[14:15]
	global_load_dwordx2 v[0:1], v[0:1], off
	s_lshl_b32 s18, s16, 7
	s_add_i32 s18, s22, s18
	v_lshl_add_u32 v2, v56, 5, s18
	v_ashrrev_i32_e32 v3, 31, v2
	v_lshlrev_b64 v[2:3], 9, v[2:3]
	s_and_b32 s17, s28, 3
	s_lshl_b32 s12, s25, 2
	v_mov_b32_e32 v54, 0
	v_lshl_add_u64 v[2:3], v[32:33], 0, v[2:3]
	v_mov_b32_e32 v6, 0
	s_waitcnt vmcnt(0)
	v_pk_mov_b32 v[4:5], v[0:1], v[0:1] op_sel:[1,0]

; #define LAS __attribute__((address_space(3)))
; __device__ __forceinline__ unsigned cvt_pk_bf16(float lo, float hi) { const f32x2 v = {lo, hi}; return __builtin_bit_cast(unsigned, __builtin_convertvector(v, bfx2_t)); }
; template <int PASS> __device__ void ssm_pass(const Params& P, int l, LAS unsigned char* lds) {
;     ...
;         f32x2 sv = {sr, si}; const f32x2 axx = {a.x, a.x}, ayn = {-a.y, a.y};
;         const bf16_t* zrow = z + (tok0 + fr) * DM + g * 16 + 4 * fq;
;         u32x2 ucur = *(const u32x2*)zrow;
; #pragma nounroll
;         for (int mt = 0; mt < 64; ++mt) {
;             u32x2 unext = ucur; if (mt < 63) unext = *(const u32x2*)(zrow + (size_t)(mt + 1) * 16 * DM);
;             const bf16x4 af = __builtin_bit_cast(bf16x4, ucur);
;             f32x4 d[8];
; #pragma unroll
;             for (int t = 0; t < 8; ++t) d[t] = __builtin_amdgcn_mfma_f32_16x16x16bf16_1k(af, bf[t], (f32x4){0.f, 0.f, 0.f, 0.f}, 0, 0, 0);
; #pragma unroll
;             for (int tq = 0; tq < 4; ++tq)
; #pragma unroll
;                 for (int j = 0; j < 4; ++j) *(LAS f32x2*)(BU + (4 * fq + j) * 528 + (16 * tq + fr) * 8) = (f32x2){d[tq][j], d[tq + 4][j]};
;             asm volatile("s_waitcnt lgkmcnt(0)" ::: "memory");
; #pragma unroll
;             for (int j = 0; j < 16; ++j) {
;                 const f32x2 bu = *(const LAS f32x2*)(BU + j * 528 + lane * 8);
;                 sv = __builtin_elementwise_fma(ayn, __builtin_shufflevector(sv, sv, 1, 0), __builtin_elementwise_fma(axx, sv, bu));
;                 if (PASS == 2) *(LAS unsigned*)(SI + j * 272 + lane * 4) = cvt_pk_bf16(sv.x, sv.y);
;             }
;             if (PASS == 2) {
;                 asm volatile("s_waitcnt lgkmcnt(0)" ::: "memory");
;                 f32x4 acc = (f32x4){0.f, 0.f, 0.f, 0.f};
; #pragma unroll
;                 for (int kt = 0; kt < 4; ++kt) { const bf16x8 sv = *(const LAS bf16x8*)(SI + fr * 272 + (32 * kt + 8 * fq) * 2);
;                     acc = __builtin_amdgcn_mfma_f32_16x16x32_bf16(cf[kt], sv, acc, 0, 0, 0); }
.LBB0_329:
	s_ashr_i32 s17, s16, 31
	s_lshl_b32 s13, s13, 10
	s_lshl_b64 s[18:19], s[16:17], 12
	s_or_b32 s16, s18, s13
	s_ashr_i32 s13, s12, 31
	s_lshl_b64 s[36:37], s[12:13], 10
	v_lshl_add_u64 v[0:1], v[26:27], 0, s[36:37]
	s_or_b32 s36, s12, 1
	s_ashr_i32 s37, s36, 31
	s_lshl_b64 s[36:37], s[36:37], 10
	v_lshl_add_u64 v[4:5], v[26:27], 0, s[36:37]
	s_or_b32 s36, s12, 2
	s_or_b32 s12, s12, 3
	s_ashr_i32 s13, s12, 31
	s_lshl_b64 s[12:13], s[12:13], 10
	v_lshl_add_u64 v[12:13], v[26:27], 0, s[12:13]
	s_lshl_b32 s12, s25, 4
	v_mov_b32_e32 v19, s19
	v_or_b32_e32 v18, s16, v20
	s_ashr_i32 s13, s12, 31
	v_lshlrev_b64 v[18:19], 11, v[18:19]
	s_ashr_i32 s37, s36, 31
	v_lshl_add_u64 v[16:17], s[12:13], 2, v[28:29]
	v_lshl_add_u64 v[18:19], s[94:95], 0, v[18:19]
	s_lshl_b64 s[12:13], s[12:13], 1
	s_lshl_b64 s[36:37], s[36:37], 10
	v_lshl_add_u64 v[18:19], v[18:19], 0, s[12:13]
	v_lshl_add_u64 v[8:9], v[26:27], 0, s[36:37]
	v_lshl_add_u64 v[18:19], v[18:19], 0, v[168:169]
	global_load_dwordx4 v[0:3], v[0:1], off
	s_nop 0
	global_load_dwordx4 v[4:7], v[4:5], off
	s_nop 0
	global_load_dwordx4 v[8:11], v[8:9], off
	s_nop 0
	global_load_dwordx4 v[12:15], v[12:13], off
	s_nop 0
	global_load_dwordx2 v[64:65], v[18:19], off
	s_nop 0
	global_load_dwordx4 v[16:19], v[16:17], off
	s_and_b32 s25, s28, 3
	v_or_b32_e32 v62, s18, v20
	v_lshl_add_u32 v60, v56, 7, s23
	v_mov_b32_e32 v63, s19
	v_lshl_or_b32 v62, s25, 10, v62
	v_ashrrev_i32_e32 v61, 31, v60
	v_lshlrev_b64 v[62:63], 11, v[62:63]
	v_lshl_add_u64 v[60:61], v[60:61], 1, v[62:63]
	s_mov_b32 s17, s19
	s_waitcnt vmcnt(0)
	v_mov_b32_e32 v56, v36
	v_mov_b32_e32 v57, v36
	v_xor_b32_e32 v36, 0x80000000, v37
	v_lshl_add_u64 v[58:59], v[30:31], 0, s[12:13]
	v_lshl_add_u64 v[60:61], v[34:35], 0, v[60:61]
	s_mov_b64 s[12:13], 0
	v_mov_b64_e32 v[62:63], v[64:65]
	v_add_u32_e32 v242, 0x2100, v68
	v_add_u32_e32 v243, 0x440, v242
	v_add_u32_e32 v244, 0x880, v242
	v_add_u32_e32 v245, 0xcc0, v242
	v_or_b32_e32 v73, s17, v21
	v_or_b32_e32 v72, s16, v20
	v_lshlrev_b64 v[70:71], 10, v[72:73]
	v_lshl_add_u64 v[246:247], v[58:59], 0, v[70:71]
	v_and_b32_e32 v70, 48, v208
	v_lshrrev_b32_e32 v70, 1, v70
	v_lshl_add_u32 v71, v20, 5, s21
	v_add_u32_e32 v146, v71, v70
	v_bfe_u32 v71, v208, 2, 1
	v_xor_b32_e32 v73, 1, v71
	v_mov_b32_e32 v72, v71
	v_and_b32_e32 v70, 3, v208
	v_lshrrev_b32_e32 v74, 1, v208
	v_and_b32_e32 v74, 12, v74
	v_add_u32_e32 v70, v70, v74
	v_lshl_add_u32 v70, v70, 5, s21
	v_and_b32_e32 v71, 32, v208
	v_lshrrev_b32_e32 v71, 1, v71
	v_add_u32_e32 v70, v70, v71
	v_mov_b32_e32 v71, s21
	v_add_u32_e32 v71, 0x200, v71
	v_cmp_eq_u32_e32 vcc, 0, v72
	s_nop 1
	v_cndmask_b32_e32 v196, v71, v70, vcc
	v_cmp_eq_u32_e32 vcc, 0, v73
	s_nop 1
	v_cndmask_b32_e32 v197, v71, v70, vcc
	v_mov_b32_e32 v72, 0
	v_mov_b32_e32 v73, 0
	v_mov_b32_e32 v74, 0
	v_mov_b32_e32 v75, 0
	v_lshl_add_u32 v70, v208, 4, s21
	ds_write_b128 v70, v[72:75] offset:512
	ds_write_b64 v146, v[64:65]
	ds_read_b128 v[156:159], v196
	ds_read_b128 v[200:203], v197
	s_mov_b64 s[18:19], 0x8000
	global_load_dwordx2 v[62:63], v[60:61], off
	global_load_dwordx2 v[150:151], v[60:61], off
	v_lshl_add_u64 v[60:61], v[60:61], 0, s[18:19]
	global_load_dwordx2 v[136:137], v[60:61], off
	global_load_dwordx2 v[150:151], v[60:61], off
	v_lshl_add_u64 v[60:61], v[60:61], 0, s[18:19]
	global_load_dwordx2 v[138:139], v[60:61], off
	global_load_dwordx2 v[150:151], v[60:61], off
	v_lshl_add_u64 v[60:61], v[60:61], 0, s[18:19]
	global_load_dwordx2 v[140:141], v[60:61], off
	global_load_dwordx2 v[150:151], v[60:61], off
	v_lshl_add_u64 v[60:61], v[60:61], 0, s[18:19]
	global_load_dwordx2 v[142:143], v[60:61], off
	global_load_dwordx2 v[150:151], v[60:61], off
	v_lshl_add_u64 v[60:61], v[60:61], 0, s[18:19]
	s_waitcnt lgkmcnt(0)
	v_mfma_f32_32x32x16_bf16 v[88:103], v[156:159], v[38:41], 0
	v_mfma_f32_32x32x16_bf16 v[104:119], v[156:159], v[46:49], 0
	v_mfma_f32_32x32x16_bf16 v[88:103], v[200:203], v[42:45], v[88:103]
	v_mfma_f32_32x32x16_bf16 v[104:119], v[200:203], v[50:53], v[104:119]
	s_nop 7
.Lp2_loop:
	s_waitcnt vmcnt(9)
	ds_write_b64 v146, v[62:63]
	ds_read_b128 v[192:195], v69 offset:8448
	ds_read_b128 v[204:207], v69 offset:8512
	ds_read_b128 v[212:215], v69 offset:8576
	ds_read_b128 v[216:219], v69 offset:8640
	ds_read_b128 v[156:159], v196
	ds_read_b128 v[200:203], v197
	global_load_dwordx2 v[144:145], v[60:61], off
	v_lshl_add_u64 v[60:61], v[60:61], 0, s[18:19]
	v_fma_f32 v70, v56, v54, v88
	v_fma_f32 v71, v56, v55, v104
	v_lshlrev_b32_e32 v76, 16, v148
	v_fma_f32 v72, v36, v55, v70
	v_fma_f32 v73, v37, v54, v71
	v_cvt_pk_bf16_f32 v74, v72, v73
	v_and_b32_e32 v77, 0xffff0000, v148
	v_fma_f32 v70, v56, v72, v89
	v_fma_f32 v71, v56, v73, v105
	v_lshlrev_b32_e32 v78, 16, v149
	v_fma_f32 v54, v36, v73, v70
	v_fma_f32 v55, v37, v72, v71
	v_cvt_pk_bf16_f32 v75, v54, v55
	v_and_b32_e32 v79, 0xffff0000, v149
	ds_write2_b32 v242, v74, v75 offset0:0 offset1:68
	s_waitcnt lgkmcnt(3)
	v_mfma_f32_16x16x32_bf16 v[220:223], v[0:3], v[192:195], 0
	v_mfma_f32_16x16x32_bf16 v[220:223], v[4:7], v[204:207], v[220:223]
	v_mfma_f32_16x16x32_bf16 v[220:223], v[8:11], v[212:215], v[220:223]
	v_mfma_f32_16x16x32_bf16 v[220:223], v[12:15], v[216:219], v[220:223]
	v_fma_f32 v70, v56, v54, v90
	v_fma_f32 v71, v56, v55, v106
	v_fma_f32 v72, v36, v55, v70
	v_fma_f32 v73, v37, v54, v71
	v_cvt_pk_bf16_f32 v74, v72, v73
	v_fma_f32 v70, v56, v72, v91
	v_fma_f32 v71, v56, v73, v107
	v_fma_f32 v54, v36, v73, v70
	v_fma_f32 v55, v37, v72, v71
	v_cvt_pk_bf16_f32 v75, v54, v55
	ds_write2_b32 v242, v74, v75 offset0:136 offset1:204
	s_waitcnt lgkmcnt(2)
; #define LAS __attribute__((address_space(3)))
; __device__ __forceinline__ unsigned cvt_pk_bf16(float lo, float hi) { const f32x2 v = {lo, hi}; return __builtin_bit_cast(unsigned, __builtin_convertvector(v, bfx2_t)); }
; template <int PASS> __device__ void ssm_pass(const Params& P, int l, LAS unsigned char* lds) {
;     ...
;         for (int mt = 0; mt < 64; ++mt) {
;             u32x2 unext = ucur; if (mt < 63) unext = *(const u32x2*)(zrow + (size_t)(mt + 1) * 16 * DM);
;             const bf16x4 af = __builtin_bit_cast(bf16x4, ucur);
;             f32x4 d[8];
; #pragma unroll
;             for (int t = 0; t < 8; ++t) d[t] = __builtin_amdgcn_mfma_f32_16x16x16bf16_1k(af, bf[t], (f32x4){0.f, 0.f, 0.f, 0.f}, 0, 0, 0);
; #pragma unroll
;             for (int tq = 0; tq < 4; ++tq)
; #pragma unroll
;                 for (int j = 0; j < 4; ++j) *(LAS f32x2*)(BU + (4 * fq + j) * 528 + (16 * tq + fr) * 8) = (f32x2){d[tq][j], d[tq + 4][j]};
;             asm volatile("s_waitcnt lgkmcnt(0)" ::: "memory");
; #pragma unroll
;             for (int j = 0; j < 16; ++j) {
;                 const f32x2 bu = *(const LAS f32x2*)(BU + j * 528 + lane * 8);
;                 sv = __builtin_elementwise_fma(ayn, __builtin_shufflevector(sv, sv, 1, 0), __builtin_elementwise_fma(axx, sv, bu));
;                 if (PASS == 2) *(LAS unsigned*)(SI + j * 272 + lane * 4) = cvt_pk_bf16(sv.x, sv.y);
;             }
;             if (PASS == 2) {
;                 asm volatile("s_waitcnt lgkmcnt(0)" ::: "memory");
;                 f32x4 acc = (f32x4){0.f, 0.f, 0.f, 0.f};
; #pragma unroll
;                 for (int kt = 0; kt < 4; ++kt) { const bf16x8 sv = *(const LAS bf16x8*)(SI + fr * 272 + (32 * kt + 8 * fq) * 2);
;                     acc = __builtin_amdgcn_mfma_f32_16x16x32_bf16(cf[kt], sv, acc, 0, 0, 0); }
;                 const size_t tok = tok0 + 16 * mt + fr;
;                 float o[4];
;                 const float uf[4] = {bflo(ucur.x), bfhi(ucur.x), bflo(ucur.y), bfhi(ucur.y)};
; #pragma unroll
;                 for (int j = 0; j < 4; ++j) { const float y = acc[j] + dd[j] * uf[j]; o[j] = y * fsigmoid(1.5957691216057308f * (y + 0.044715f * y * y * y)); }
;                 u32x2 w; w.x = cvt_pk_bf16(o[0], o[1]); w.y = cvt_pk_bf16(o[2], o[3]);
;                 *(u32x2*)(ypre + tok * 512 + g * 16 + 4 * fq) = w;
;             }
	v_mfma_f32_32x32x16_bf16 v[120:135], v[156:159], v[38:41], 0
	v_mfma_f32_32x32x16_bf16 v[226:241], v[156:159], v[46:49], 0
	v_fma_f32 v70, v56, v54, v92
	v_fma_f32 v71, v56, v55, v108
	v_fma_f32 v80, v16, v76, v220
	v_fma_f32 v81, v17, v77, v221
	v_fma_f32 v72, v36, v55, v70
	v_fma_f32 v73, v37, v54, v71
	v_cvt_pk_bf16_f32 v74, v72, v73
	v_fma_f32 v82, v18, v78, v222
	v_fma_f32 v83, v19, v79, v223
	v_fma_f32 v70, v56, v72, v93
	v_fma_f32 v71, v56, v73, v109
	v_mul_f32_e32 v84, 0x3d372713, v80
	v_mul_f32_e32 v85, 0x3d372713, v81
	v_fma_f32 v54, v36, v73, v70
	v_fma_f32 v55, v37, v72, v71
	v_cvt_pk_bf16_f32 v75, v54, v55
	v_mul_f32_e32 v86, 0x3d372713, v82
	v_mul_f32_e32 v87, 0x3d372713, v83
	ds_write2_b32 v243, v74, v75 offset0:0 offset1:68
	v_mfma_f32_32x32x16_bf16 v[120:135], v[200:203], v[42:45], v[120:135]
	v_mfma_f32_32x32x16_bf16 v[226:241], v[200:203], v[50:53], v[226:241]
	v_fma_f32 v70, v56, v54, v94
	v_fma_f32 v71, v56, v55, v110
	v_mul_f32_e32 v84, v80, v84
	v_mul_f32_e32 v85, v81, v85
	v_fma_f32 v72, v36, v55, v70
	v_fma_f32 v73, v37, v54, v71
	v_cvt_pk_bf16_f32 v74, v72, v73
	v_mul_f32_e32 v86, v82, v86
	v_mul_f32_e32 v87, v83, v87
	v_fma_f32 v70, v56, v72, v95
	v_fma_f32 v71, v56, v73, v111
	v_fma_f32 v84, v80, v84, v80
	v_fma_f32 v85, v81, v85, v81
	v_fma_f32 v54, v36, v73, v70
	v_fma_f32 v55, v37, v72, v71
	v_cvt_pk_bf16_f32 v75, v54, v55
	v_fma_f32 v86, v82, v86, v82
	v_fma_f32 v87, v83, v87, v83
	ds_write2_b32 v243, v74, v75 offset0:136 offset1:204
	v_fma_f32 v70, v56, v54, v96
	v_fma_f32 v71, v56, v55, v112
	v_mul_f32_e32 v84, 0x3fcc422a, v84
	v_mul_f32_e32 v85, 0x3fcc422a, v85
	v_fma_f32 v72, v36, v55, v70
	v_fma_f32 v73, v37, v54, v71
	v_cvt_pk_bf16_f32 v74, v72, v73
	v_mul_f32_e32 v86, 0x3fcc422a, v86
	v_mul_f32_e32 v87, 0x3fcc422a, v87
	v_fma_f32 v70, v56, v72, v97
	v_fma_f32 v71, v56, v73, v113
	v_mul_f32_e32 v84, 0xbfb8aa3b, v84
	v_mul_f32_e32 v85, 0xbfb8aa3b, v85
	v_fma_f32 v54, v36, v73, v70
	v_fma_f32 v55, v37, v72, v71
	v_cvt_pk_bf16_f32 v75, v54, v55
	v_mul_f32_e32 v86, 0xbfb8aa3b, v86
	ds_write2_b32 v244, v74, v75 offset0:0 offset1:68
	v_fma_f32 v70, v56, v54, v98
	v_fma_f32 v71, v56, v55, v114
	v_mul_f32_e32 v87, 0xbfb8aa3b, v87
	v_exp_f32_e32 v84, v84
	v_fma_f32 v72, v36, v55, v70
	v_fma_f32 v73, v37, v54, v71
	v_cvt_pk_bf16_f32 v74, v72, v73
	v_exp_f32_e32 v85, v85
	v_exp_f32_e32 v86, v86
	v_fma_f32 v70, v56, v72, v99
	v_fma_f32 v71, v56, v73, v115
	v_exp_f32_e32 v87, v87
	v_add_f32_e32 v84, 1.0, v84
	v_fma_f32 v54, v36, v73, v70
	v_fma_f32 v55, v37, v72, v71
	v_cvt_pk_bf16_f32 v75, v54, v55
	v_add_f32_e32 v85, 1.0, v85
	ds_write2_b32 v244, v74, v75 offset0:136 offset1:204
	v_fma_f32 v70, v56, v54, v100
	v_fma_f32 v71, v56, v55, v116
	v_add_f32_e32 v86, 1.0, v86
	v_add_f32_e32 v87, 1.0, v87
	v_fma_f32 v72, v36, v55, v70
	v_fma_f32 v73, v37, v54, v71
	v_cvt_pk_bf16_f32 v74, v72, v73
	v_rcp_f32_e32 v84, v84
	v_rcp_f32_e32 v85, v85
	v_fma_f32 v70, v56, v72, v101
	v_fma_f32 v71, v56, v73, v117
	v_rcp_f32_e32 v86, v86
	v_rcp_f32_e32 v87, v87
	v_fma_f32 v54, v36, v73, v70
	v_fma_f32 v55, v37, v72, v71
	v_cvt_pk_bf16_f32 v75, v54, v55
	s_nop 0
	ds_write2_b32 v245, v74, v75 offset0:0 offset1:68
	v_fma_f32 v70, v56, v54, v102
	v_fma_f32 v71, v56, v55, v118
	v_mul_f32_e32 v84, v80, v84
	v_mul_f32_e32 v85, v81, v85
	v_fma_f32 v72, v36, v55, v70
	v_fma_f32 v73, v37, v54, v71
	v_cvt_pk_bf16_f32 v74, v72, v73
	v_mul_f32_e32 v86, v82, v86
	v_mul_f32_e32 v87, v83, v87
	v_fma_f32 v70, v56, v72, v103
	v_fma_f32 v71, v56, v73, v119
	v_cvt_pk_bf16_f32 v84, v84, v85
	v_fma_f32 v54, v36, v73, v70
	v_fma_f32 v55, v37, v72, v71
	v_cvt_pk_bf16_f32 v75, v54, v55
	v_cvt_pk_bf16_f32 v85, v86, v87
	ds_write2_b32 v245, v74, v75 offset0:136 offset1:204
	s_cmp_eq_u32 s12, 0
	s_cbranch_scc1 .Lp2_skip
	global_store_dwordx2 v[246:247], v[84:85], off
	s_mov_b64 s[18:19], 0x4000
	v_lshl_add_u64 v[246:247], v[246:247], 0, s[18:19]
	s_mov_b64 s[18:19], 0x8000
	s_branch .Lp2_join
.Lp2_skip:
	global_load_dwordx2 v[150:151], v[60:61], off
.Lp2_join:
	s_waitcnt vmcnt(9)
	ds_write_b64 v146, v[136:137]
	ds_read_b128 v[192:195], v69 offset:8448
	ds_read_b128 v[204:207], v69 offset:8512
	ds_read_b128 v[212:215], v69 offset:8576
	ds_read_b128 v[216:219], v69 offset:8640
	ds_read_b128 v[156:159], v196
	ds_read_b128 v[200:203], v197
	global_load_dwordx2 v[148:149], v[60:61], off
	v_lshl_add_u64 v[60:61], v[60:61], 0, s[18:19]
	v_fma_f32 v70, v56, v54, v120
	v_fma_f32 v71, v56, v55, v226
	v_lshlrev_b32_e32 v76, 16, v64
	v_fma_f32 v72, v36, v55, v70
	v_fma_f32 v73, v37, v54, v71
	v_cvt_pk_bf16_f32 v74, v72, v73
	v_and_b32_e32 v77, 0xffff0000, v64
	v_fma_f32 v70, v56, v72, v121
	v_fma_f32 v71, v56, v73, v227
	v_lshlrev_b32_e32 v78, 16, v65
	v_fma_f32 v54, v36, v73, v70
	v_fma_f32 v55, v37, v72, v71
	v_cvt_pk_bf16_f32 v75, v54, v55
	v_and_b32_e32 v79, 0xffff0000, v65
	ds_write2_b32 v242, v74, v75 offset0:0 offset1:68
	s_waitcnt lgkmcnt(3)
	v_mfma_f32_16x16x32_bf16 v[220:223], v[0:3], v[192:195], 0
	v_mfma_f32_16x16x32_bf16 v[220:223], v[4:7], v[204:207], v[220:223]
	v_mfma_f32_16x16x32_bf16 v[220:223], v[8:11], v[212:215], v[220:223]
	v_mfma_f32_16x16x32_bf16 v[220:223], v[12:15], v[216:219], v[220:223]
	v_fma_f32 v70, v56, v54, v122
	v_fma_f32 v71, v56, v55, v228
	v_fma_f32 v72, v36, v55, v70
	v_fma_f32 v73, v37, v54, v71
	v_cvt_pk_bf16_f32 v74, v72, v73
	v_fma_f32 v70, v56, v72, v123
	v_fma_f32 v71, v56, v73, v229
	v_fma_f32 v54, v36, v73, v70
	v_fma_f32 v55, v37, v72, v71
	v_cvt_pk_bf16_f32 v75, v54, v55
	ds_write2_b32 v242, v74, v75 offset0:136 offset1:204
	s_waitcnt lgkmcnt(2)
; #define LAS __attribute__((address_space(3)))
; __device__ __forceinline__ unsigned cvt_pk_bf16(float lo, float hi) { const f32x2 v = {lo, hi}; return __builtin_bit_cast(unsigned, __builtin_convertvector(v, bfx2_t)); }
; template <int PASS> __device__ void ssm_pass(const Params& P, int l, LAS unsigned char* lds) {
;     ...
;         for (int mt = 0; mt < 64; ++mt) {
;             u32x2 unext = ucur; if (mt < 63) unext = *(const u32x2*)(zrow + (size_t)(mt + 1) * 16 * DM);
;             const bf16x4 af = __builtin_bit_cast(bf16x4, ucur);
;             f32x4 d[8];
; #pragma unroll
;             for (int t = 0; t < 8; ++t) d[t] = __builtin_amdgcn_mfma_f32_16x16x16bf16_1k(af, bf[t], (f32x4){0.f, 0.f, 0.f, 0.f}, 0, 0, 0);
; #pragma unroll
;             for (int tq = 0; tq < 4; ++tq)
; #pragma unroll
;                 for (int j = 0; j < 4; ++j) *(LAS f32x2*)(BU + (4 * fq + j) * 528 + (16 * tq + fr) * 8) = (f32x2){d[tq][j], d[tq + 4][j]};
;             asm volatile("s_waitcnt lgkmcnt(0)" ::: "memory");
; #pragma unroll
;             for (int j = 0; j < 16; ++j) {
;                 const f32x2 bu = *(const LAS f32x2*)(BU + j * 528 + lane * 8);
;                 sv = __builtin_elementwise_fma(ayn, __builtin_shufflevector(sv, sv, 1, 0), __builtin_elementwise_fma(axx, sv, bu));
;                 if (PASS == 2) *(LAS unsigned*)(SI + j * 272 + lane * 4) = cvt_pk_bf16(sv.x, sv.y);
;             }
;             if (PASS == 2) {
;                 asm volatile("s_waitcnt lgkmcnt(0)" ::: "memory");
;                 f32x4 acc = (f32x4){0.f, 0.f, 0.f, 0.f};
; #pragma unroll
;                 for (int kt = 0; kt < 4; ++kt) { const bf16x8 sv = *(const LAS bf16x8*)(SI + fr * 272 + (32 * kt + 8 * fq) * 2);
;                     acc = __builtin_amdgcn_mfma_f32_16x16x32_bf16(cf[kt], sv, acc, 0, 0, 0); }
;                 const size_t tok = tok0 + 16 * mt + fr;
;                 float o[4];
;                 const float uf[4] = {bflo(ucur.x), bfhi(ucur.x), bflo(ucur.y), bfhi(ucur.y)};
; #pragma unroll
;                 for (int j = 0; j < 4; ++j) { const float y = acc[j] + dd[j] * uf[j]; o[j] = y * fsigmoid(1.5957691216057308f * (y + 0.044715f * y * y * y)); }
;                 u32x2 w; w.x = cvt_pk_bf16(o[0], o[1]); w.y = cvt_pk_bf16(o[2], o[3]);
;                 *(u32x2*)(ypre + tok * 512 + g * 16 + 4 * fq) = w;
;             }
	v_mfma_f32_32x32x16_bf16 v[88:103], v[156:159], v[38:41], 0
	v_mfma_f32_32x32x16_bf16 v[104:119], v[156:159], v[46:49], 0
	v_fma_f32 v70, v56, v54, v124
	v_fma_f32 v71, v56, v55, v230
	v_fma_f32 v80, v16, v76, v220
	v_fma_f32 v81, v17, v77, v221
	v_fma_f32 v72, v36, v55, v70
	v_fma_f32 v73, v37, v54, v71
	v_cvt_pk_bf16_f32 v74, v72, v73
	v_fma_f32 v82, v18, v78, v222
	v_fma_f32 v83, v19, v79, v223
	v_fma_f32 v70, v56, v72, v125
	v_fma_f32 v71, v56, v73, v231
	v_mul_f32_e32 v84, 0x3d372713, v80
	v_mul_f32_e32 v85, 0x3d372713, v81
	v_fma_f32 v54, v36, v73, v70
	v_fma_f32 v55, v37, v72, v71
	v_cvt_pk_bf16_f32 v75, v54, v55
	v_mul_f32_e32 v86, 0x3d372713, v82
	v_mul_f32_e32 v87, 0x3d372713, v83
	ds_write2_b32 v243, v74, v75 offset0:0 offset1:68
	v_mfma_f32_32x32x16_bf16 v[88:103], v[200:203], v[42:45], v[88:103]
	v_mfma_f32_32x32x16_bf16 v[104:119], v[200:203], v[50:53], v[104:119]
	v_fma_f32 v70, v56, v54, v126
	v_fma_f32 v71, v56, v55, v232
	v_mul_f32_e32 v84, v80, v84
	v_mul_f32_e32 v85, v81, v85
	v_fma_f32 v72, v36, v55, v70
	v_fma_f32 v73, v37, v54, v71
	v_cvt_pk_bf16_f32 v74, v72, v73
	v_mul_f32_e32 v86, v82, v86
	v_mul_f32_e32 v87, v83, v87
	v_fma_f32 v70, v56, v72, v127
	v_fma_f32 v71, v56, v73, v233
	v_fma_f32 v84, v80, v84, v80
	v_fma_f32 v85, v81, v85, v81
	v_fma_f32 v54, v36, v73, v70
	v_fma_f32 v55, v37, v72, v71
	v_cvt_pk_bf16_f32 v75, v54, v55
	v_fma_f32 v86, v82, v86, v82
	v_fma_f32 v87, v83, v87, v83
	ds_write2_b32 v243, v74, v75 offset0:136 offset1:204
	v_fma_f32 v70, v56, v54, v128
	v_fma_f32 v71, v56, v55, v234
	v_mul_f32_e32 v84, 0x3fcc422a, v84
	v_mul_f32_e32 v85, 0x3fcc422a, v85
	v_fma_f32 v72, v36, v55, v70
	v_fma_f32 v73, v37, v54, v71
	v_cvt_pk_bf16_f32 v74, v72, v73
	v_mul_f32_e32 v86, 0x3fcc422a, v86
	v_mul_f32_e32 v87, 0x3fcc422a, v87
	v_fma_f32 v70, v56, v72, v129
	v_fma_f32 v71, v56, v73, v235
	v_mul_f32_e32 v84, 0xbfb8aa3b, v84
	v_mul_f32_e32 v85, 0xbfb8aa3b, v85
	v_fma_f32 v54, v36, v73, v70
	v_fma_f32 v55, v37, v72, v71
	v_cvt_pk_bf16_f32 v75, v54, v55
	v_mul_f32_e32 v86, 0xbfb8aa3b, v86
	ds_write2_b32 v244, v74, v75 offset0:0 offset1:68
	v_fma_f32 v70, v56, v54, v130
	v_fma_f32 v71, v56, v55, v236
	v_mul_f32_e32 v87, 0xbfb8aa3b, v87
	v_exp_f32_e32 v84, v84
	v_fma_f32 v72, v36, v55, v70
	v_fma_f32 v73, v37, v54, v71
	v_cvt_pk_bf16_f32 v74, v72, v73
	v_exp_f32_e32 v85, v85
	v_exp_f32_e32 v86, v86
	v_fma_f32 v70, v56, v72, v131
	v_fma_f32 v71, v56, v73, v237
	v_exp_f32_e32 v87, v87
	v_add_f32_e32 v84, 1.0, v84
	v_fma_f32 v54, v36, v73, v70
	v_fma_f32 v55, v37, v72, v71
	v_cvt_pk_bf16_f32 v75, v54, v55
	v_add_f32_e32 v85, 1.0, v85
	ds_write2_b32 v244, v74, v75 offset0:136 offset1:204
	v_fma_f32 v70, v56, v54, v132
	v_fma_f32 v71, v56, v55, v238
	v_add_f32_e32 v86, 1.0, v86
	v_add_f32_e32 v87, 1.0, v87
	v_fma_f32 v72, v36, v55, v70
	v_fma_f32 v73, v37, v54, v71
	v_cvt_pk_bf16_f32 v74, v72, v73
	v_rcp_f32_e32 v84, v84
	v_rcp_f32_e32 v85, v85
	v_fma_f32 v70, v56, v72, v133
	v_fma_f32 v71, v56, v73, v239
	v_rcp_f32_e32 v86, v86
	v_rcp_f32_e32 v87, v87
	v_fma_f32 v54, v36, v73, v70
	v_fma_f32 v55, v37, v72, v71
	v_cvt_pk_bf16_f32 v75, v54, v55
	s_nop 0
	ds_write2_b32 v245, v74, v75 offset0:0 offset1:68
	v_fma_f32 v70, v56, v54, v134
	v_fma_f32 v71, v56, v55, v240
	v_mul_f32_e32 v84, v80, v84
	v_mul_f32_e32 v85, v81, v85
	v_fma_f32 v72, v36, v55, v70
	v_fma_f32 v73, v37, v54, v71
	v_cvt_pk_bf16_f32 v74, v72, v73
	v_mul_f32_e32 v86, v82, v86
	v_mul_f32_e32 v87, v83, v87
	v_fma_f32 v70, v56, v72, v135
	v_fma_f32 v71, v56, v73, v241
	v_cvt_pk_bf16_f32 v84, v84, v85
	v_fma_f32 v54, v36, v73, v70
	v_fma_f32 v55, v37, v72, v71
	v_cvt_pk_bf16_f32 v75, v54, v55
	v_cvt_pk_bf16_f32 v85, v86, v87
	ds_write2_b32 v245, v74, v75 offset0:136 offset1:204
	global_store_dwordx2 v[246:247], v[84:85], off
	s_mov_b64 s[18:19], 0x4000
	v_lshl_add_u64 v[246:247], v[246:247], 0, s[18:19]
	s_mov_b64 s[18:19], 0x8000
	s_waitcnt vmcnt(9)
	ds_write_b64 v146, v[138:139]
	ds_read_b128 v[192:195], v69 offset:8448
	ds_read_b128 v[204:207], v69 offset:8512
	ds_read_b128 v[212:215], v69 offset:8576
	ds_read_b128 v[216:219], v69 offset:8640
	ds_read_b128 v[156:159], v196
	ds_read_b128 v[200:203], v197
	global_load_dwordx2 v[64:65], v[60:61], off
	v_lshl_add_u64 v[60:61], v[60:61], 0, s[18:19]
	v_fma_f32 v70, v56, v54, v88
	v_fma_f32 v71, v56, v55, v104
	v_lshlrev_b32_e32 v76, 16, v62
	v_fma_f32 v72, v36, v55, v70
	v_fma_f32 v73, v37, v54, v71
	v_cvt_pk_bf16_f32 v74, v72, v73
	v_and_b32_e32 v77, 0xffff0000, v62
	v_fma_f32 v70, v56, v72, v89
	v_fma_f32 v71, v56, v73, v105
	v_lshlrev_b32_e32 v78, 16, v63
	v_fma_f32 v54, v36, v73, v70
	v_fma_f32 v55, v37, v72, v71
	v_cvt_pk_bf16_f32 v75, v54, v55
	v_and_b32_e32 v79, 0xffff0000, v63
	ds_write2_b32 v242, v74, v75 offset0:0 offset1:68
	s_waitcnt lgkmcnt(3)
	v_mfma_f32_16x16x32_bf16 v[220:223], v[0:3], v[192:195], 0
	v_mfma_f32_16x16x32_bf16 v[220:223], v[4:7], v[204:207], v[220:223]
	v_mfma_f32_16x16x32_bf16 v[220:223], v[8:11], v[212:215], v[220:223]
	v_mfma_f32_16x16x32_bf16 v[220:223], v[12:15], v[216:219], v[220:223]
	v_fma_f32 v70, v56, v54, v90
	v_fma_f32 v71, v56, v55, v106
	v_fma_f32 v72, v36, v55, v70
	v_fma_f32 v73, v37, v54, v71
	v_cvt_pk_bf16_f32 v74, v72, v73
	v_fma_f32 v70, v56, v72, v91
	v_fma_f32 v71, v56, v73, v107
	v_fma_f32 v54, v36, v73, v70
	v_fma_f32 v55, v37, v72, v71
	v_cvt_pk_bf16_f32 v75, v54, v55
	ds_write2_b32 v242, v74, v75 offset0:136 offset1:204
	s_waitcnt lgkmcnt(2)
; #define LAS __attribute__((address_space(3)))
; __device__ __forceinline__ unsigned cvt_pk_bf16(float lo, float hi) { const f32x2 v = {lo, hi}; return __builtin_bit_cast(unsigned, __builtin_convertvector(v, bfx2_t)); }
; template <int PASS> __device__ void ssm_pass(const Params& P, int l, LAS unsigned char* lds) {
;     ...
;         for (int mt = 0; mt < 64; ++mt) {
;             u32x2 unext = ucur; if (mt < 63) unext = *(const u32x2*)(zrow + (size_t)(mt + 1) * 16 * DM);
;             const bf16x4 af = __builtin_bit_cast(bf16x4, ucur);
;             f32x4 d[8];
; #pragma unroll
;             for (int t = 0; t < 8; ++t) d[t] = __builtin_amdgcn_mfma_f32_16x16x16bf16_1k(af, bf[t], (f32x4){0.f, 0.f, 0.f, 0.f}, 0, 0, 0);
; #pragma unroll
;             for (int tq = 0; tq < 4; ++tq)
; #pragma unroll
;                 for (int j = 0; j < 4; ++j) *(LAS f32x2*)(BU + (4 * fq + j) * 528 + (16 * tq + fr) * 8) = (f32x2){d[tq][j], d[tq + 4][j]};
;             asm volatile("s_waitcnt lgkmcnt(0)" ::: "memory");
; #pragma unroll
;             for (int j = 0; j < 16; ++j) {
;                 const f32x2 bu = *(const LAS f32x2*)(BU + j * 528 + lane * 8);
;                 sv = __builtin_elementwise_fma(ayn, __builtin_shufflevector(sv, sv, 1, 0), __builtin_elementwise_fma(axx, sv, bu));
;                 if (PASS == 2) *(LAS unsigned*)(SI + j * 272 + lane * 4) = cvt_pk_bf16(sv.x, sv.y);
;             }
;             if (PASS == 2) {
;                 asm volatile("s_waitcnt lgkmcnt(0)" ::: "memory");
;                 f32x4 acc = (f32x4){0.f, 0.f, 0.f, 0.f};
; #pragma unroll
;                 for (int kt = 0; kt < 4; ++kt) { const bf16x8 sv = *(const LAS bf16x8*)(SI + fr * 272 + (32 * kt + 8 * fq) * 2);
;                     acc = __builtin_amdgcn_mfma_f32_16x16x32_bf16(cf[kt], sv, acc, 0, 0, 0); }
;                 const size_t tok = tok0 + 16 * mt + fr;
;                 float o[4];
;                 const float uf[4] = {bflo(ucur.x), bfhi(ucur.x), bflo(ucur.y), bfhi(ucur.y)};
; #pragma unroll
;                 for (int j = 0; j < 4; ++j) { const float y = acc[j] + dd[j] * uf[j]; o[j] = y * fsigmoid(1.5957691216057308f * (y + 0.044715f * y * y * y)); }
;                 u32x2 w; w.x = cvt_pk_bf16(o[0], o[1]); w.y = cvt_pk_bf16(o[2], o[3]);
;                 *(u32x2*)(ypre + tok * 512 + g * 16 + 4 * fq) = w;
;             }
	v_mfma_f32_32x32x16_bf16 v[120:135], v[156:159], v[38:41], 0
	v_mfma_f32_32x32x16_bf16 v[226:241], v[156:159], v[46:49], 0
	v_fma_f32 v70, v56, v54, v92
	v_fma_f32 v71, v56, v55, v108
	v_fma_f32 v80, v16, v76, v220
	v_fma_f32 v81, v17, v77, v221
	v_fma_f32 v72, v36, v55, v70
	v_fma_f32 v73, v37, v54, v71
	v_cvt_pk_bf16_f32 v74, v72, v73
	v_fma_f32 v82, v18, v78, v222
	v_fma_f32 v83, v19, v79, v223
	v_fma_f32 v70, v56, v72, v93
	v_fma_f32 v71, v56, v73, v109
	v_mul_f32_e32 v84, 0x3d372713, v80
	v_mul_f32_e32 v85, 0x3d372713, v81
	v_fma_f32 v54, v36, v73, v70
	v_fma_f32 v55, v37, v72, v71
	v_cvt_pk_bf16_f32 v75, v54, v55
	v_mul_f32_e32 v86, 0x3d372713, v82
	v_mul_f32_e32 v87, 0x3d372713, v83
	ds_write2_b32 v243, v74, v75 offset0:0 offset1:68
	v_mfma_f32_32x32x16_bf16 v[120:135], v[200:203], v[42:45], v[120:135]
	v_mfma_f32_32x32x16_bf16 v[226:241], v[200:203], v[50:53], v[226:241]
	v_fma_f32 v70, v56, v54, v94
	v_fma_f32 v71, v56, v55, v110
	v_mul_f32_e32 v84, v80, v84
	v_mul_f32_e32 v85, v81, v85
	v_fma_f32 v72, v36, v55, v70
	v_fma_f32 v73, v37, v54, v71
	v_cvt_pk_bf16_f32 v74, v72, v73
	v_mul_f32_e32 v86, v82, v86
	v_mul_f32_e32 v87, v83, v87
	v_fma_f32 v70, v56, v72, v95
	v_fma_f32 v71, v56, v73, v111
	v_fma_f32 v84, v80, v84, v80
	v_fma_f32 v85, v81, v85, v81
	v_fma_f32 v54, v36, v73, v70
	v_fma_f32 v55, v37, v72, v71
	v_cvt_pk_bf16_f32 v75, v54, v55
	v_fma_f32 v86, v82, v86, v82
	v_fma_f32 v87, v83, v87, v83
	ds_write2_b32 v243, v74, v75 offset0:136 offset1:204
	v_fma_f32 v70, v56, v54, v96
	v_fma_f32 v71, v56, v55, v112
	v_mul_f32_e32 v84, 0x3fcc422a, v84
	v_mul_f32_e32 v85, 0x3fcc422a, v85
	v_fma_f32 v72, v36, v55, v70
	v_fma_f32 v73, v37, v54, v71
	v_cvt_pk_bf16_f32 v74, v72, v73
	v_mul_f32_e32 v86, 0x3fcc422a, v86
	v_mul_f32_e32 v87, 0x3fcc422a, v87
	v_fma_f32 v70, v56, v72, v97
	v_fma_f32 v71, v56, v73, v113
	v_mul_f32_e32 v84, 0xbfb8aa3b, v84
	v_mul_f32_e32 v85, 0xbfb8aa3b, v85
	v_fma_f32 v54, v36, v73, v70
	v_fma_f32 v55, v37, v72, v71
	v_cvt_pk_bf16_f32 v75, v54, v55
	v_mul_f32_e32 v86, 0xbfb8aa3b, v86
	ds_write2_b32 v244, v74, v75 offset0:0 offset1:68
	v_fma_f32 v70, v56, v54, v98
	v_fma_f32 v71, v56, v55, v114
	v_mul_f32_e32 v87, 0xbfb8aa3b, v87
	v_exp_f32_e32 v84, v84
	v_fma_f32 v72, v36, v55, v70
	v_fma_f32 v73, v37, v54, v71
	v_cvt_pk_bf16_f32 v74, v72, v73
	v_exp_f32_e32 v85, v85
	v_exp_f32_e32 v86, v86
	v_fma_f32 v70, v56, v72, v99
	v_fma_f32 v71, v56, v73, v115
	v_exp_f32_e32 v87, v87
	v_add_f32_e32 v84, 1.0, v84
	v_fma_f32 v54, v36, v73, v70
	v_fma_f32 v55, v37, v72, v71
	v_cvt_pk_bf16_f32 v75, v54, v55
	v_add_f32_e32 v85, 1.0, v85
	ds_write2_b32 v244, v74, v75 offset0:136 offset1:204
	v_fma_f32 v70, v56, v54, v100
	v_fma_f32 v71, v56, v55, v116
	v_add_f32_e32 v86, 1.0, v86
	v_add_f32_e32 v87, 1.0, v87
	v_fma_f32 v72, v36, v55, v70
	v_fma_f32 v73, v37, v54, v71
	v_cvt_pk_bf16_f32 v74, v72, v73
	v_rcp_f32_e32 v84, v84
	v_rcp_f32_e32 v85, v85
	v_fma_f32 v70, v56, v72, v101
	v_fma_f32 v71, v56, v73, v117
	v_rcp_f32_e32 v86, v86
	v_rcp_f32_e32 v87, v87
	v_fma_f32 v54, v36, v73, v70
	v_fma_f32 v55, v37, v72, v71
	v_cvt_pk_bf16_f32 v75, v54, v55
	s_nop 0
	ds_write2_b32 v245, v74, v75 offset0:0 offset1:68
	v_fma_f32 v70, v56, v54, v102
	v_fma_f32 v71, v56, v55, v118
	v_mul_f32_e32 v84, v80, v84
	v_mul_f32_e32 v85, v81, v85
	v_fma_f32 v72, v36, v55, v70
	v_fma_f32 v73, v37, v54, v71
	v_cvt_pk_bf16_f32 v74, v72, v73
	v_mul_f32_e32 v86, v82, v86
	v_mul_f32_e32 v87, v83, v87
	v_fma_f32 v70, v56, v72, v103
	v_fma_f32 v71, v56, v73, v119
	v_cvt_pk_bf16_f32 v84, v84, v85
	v_fma_f32 v54, v36, v73, v70
	v_fma_f32 v55, v37, v72, v71
	v_cvt_pk_bf16_f32 v75, v54, v55
	v_cvt_pk_bf16_f32 v85, v86, v87
	ds_write2_b32 v245, v74, v75 offset0:136 offset1:204
	global_store_dwordx2 v[246:247], v[84:85], off
	s_mov_b64 s[18:19], 0x4000
	v_lshl_add_u64 v[246:247], v[246:247], 0, s[18:19]
	s_mov_b64 s[18:19], 0x8000
	s_waitcnt vmcnt(9)
	ds_write_b64 v146, v[140:141]
	ds_read_b128 v[192:195], v69 offset:8448
	ds_read_b128 v[204:207], v69 offset:8512
	ds_read_b128 v[212:215], v69 offset:8576
	ds_read_b128 v[216:219], v69 offset:8640
	ds_read_b128 v[156:159], v196
	ds_read_b128 v[200:203], v197
	global_load_dwordx2 v[62:63], v[60:61], off
	v_lshl_add_u64 v[60:61], v[60:61], 0, s[18:19]
	v_fma_f32 v70, v56, v54, v120
	v_fma_f32 v71, v56, v55, v226
	v_lshlrev_b32_e32 v76, 16, v136
	v_fma_f32 v72, v36, v55, v70
	v_fma_f32 v73, v37, v54, v71
	v_cvt_pk_bf16_f32 v74, v72, v73
	v_and_b32_e32 v77, 0xffff0000, v136
	v_fma_f32 v70, v56, v72, v121
	v_fma_f32 v71, v56, v73, v227
	v_lshlrev_b32_e32 v78, 16, v137
	v_fma_f32 v54, v36, v73, v70
	v_fma_f32 v55, v37, v72, v71
	v_cvt_pk_bf16_f32 v75, v54, v55
	v_and_b32_e32 v79, 0xffff0000, v137
	ds_write2_b32 v242, v74, v75 offset0:0 offset1:68
	s_waitcnt lgkmcnt(3)
	v_mfma_f32_16x16x32_bf16 v[220:223], v[0:3], v[192:195], 0
	v_mfma_f32_16x16x32_bf16 v[220:223], v[4:7], v[204:207], v[220:223]
	v_mfma_f32_16x16x32_bf16 v[220:223], v[8:11], v[212:215], v[220:223]
	v_mfma_f32_16x16x32_bf16 v[220:223], v[12:15], v[216:219], v[220:223]
	v_fma_f32 v70, v56, v54, v122
	v_fma_f32 v71, v56, v55, v228
	v_fma_f32 v72, v36, v55, v70
	v_fma_f32 v73, v37, v54, v71
	v_cvt_pk_bf16_f32 v74, v72, v73
	v_fma_f32 v70, v56, v72, v123
	v_fma_f32 v71, v56, v73, v229
	v_fma_f32 v54, v36, v73, v70
	v_fma_f32 v55, v37, v72, v71
	v_cvt_pk_bf16_f32 v75, v54, v55
	ds_write2_b32 v242, v74, v75 offset0:136 offset1:204
	s_waitcnt lgkmcnt(2)
; #define LAS __attribute__((address_space(3)))
; __device__ __forceinline__ unsigned cvt_pk_bf16(float lo, float hi) { const f32x2 v = {lo, hi}; return __builtin_bit_cast(unsigned, __builtin_convertvector(v, bfx2_t)); }
; template <int PASS> __device__ void ssm_pass(const Params& P, int l, LAS unsigned char* lds) {
;     ...
;         for (int mt = 0; mt < 64; ++mt) {
;             u32x2 unext = ucur; if (mt < 63) unext = *(const u32x2*)(zrow + (size_t)(mt + 1) * 16 * DM);
;             const bf16x4 af = __builtin_bit_cast(bf16x4, ucur);
;             f32x4 d[8];
; #pragma unroll
;             for (int t = 0; t < 8; ++t) d[t] = __builtin_amdgcn_mfma_f32_16x16x16bf16_1k(af, bf[t], (f32x4){0.f, 0.f, 0.f, 0.f}, 0, 0, 0);
; #pragma unroll
;             for (int tq = 0; tq < 4; ++tq)
; #pragma unroll
;                 for (int j = 0; j < 4; ++j) *(LAS f32x2*)(BU + (4 * fq + j) * 528 + (16 * tq + fr) * 8) = (f32x2){d[tq][j], d[tq + 4][j]};
;             asm volatile("s_waitcnt lgkmcnt(0)" ::: "memory");
; #pragma unroll
;             for (int j = 0; j < 16; ++j) {
;                 const f32x2 bu = *(const LAS f32x2*)(BU + j * 528 + lane * 8);
;                 sv = __builtin_elementwise_fma(ayn, __builtin_shufflevector(sv, sv, 1, 0), __builtin_elementwise_fma(axx, sv, bu));
;                 if (PASS == 2) *(LAS unsigned*)(SI + j * 272 + lane * 4) = cvt_pk_bf16(sv.x, sv.y);
;             }
;             if (PASS == 2) {
;                 asm volatile("s_waitcnt lgkmcnt(0)" ::: "memory");
;                 f32x4 acc = (f32x4){0.f, 0.f, 0.f, 0.f};
; #pragma unroll
;                 for (int kt = 0; kt < 4; ++kt) { const bf16x8 sv = *(const LAS bf16x8*)(SI + fr * 272 + (32 * kt + 8 * fq) * 2);
;                     acc = __builtin_amdgcn_mfma_f32_16x16x32_bf16(cf[kt], sv, acc, 0, 0, 0); }
;                 const size_t tok = tok0 + 16 * mt + fr;
;                 float o[4];
;                 const float uf[4] = {bflo(ucur.x), bfhi(ucur.x), bflo(ucur.y), bfhi(ucur.y)};
; #pragma unroll
;                 for (int j = 0; j < 4; ++j) { const float y = acc[j] + dd[j] * uf[j]; o[j] = y * fsigmoid(1.5957691216057308f * (y + 0.044715f * y * y * y)); }
;                 u32x2 w; w.x = cvt_pk_bf16(o[0], o[1]); w.y = cvt_pk_bf16(o[2], o[3]);
;                 *(u32x2*)(ypre + tok * 512 + g * 16 + 4 * fq) = w;
	v_mfma_f32_32x32x16_bf16 v[88:103], v[156:159], v[38:41], 0
	v_mfma_f32_32x32x16_bf16 v[104:119], v[156:159], v[46:49], 0
	v_fma_f32 v70, v56, v54, v124
	v_fma_f32 v71, v56, v55, v230
	v_fma_f32 v80, v16, v76, v220
	v_fma_f32 v81, v17, v77, v221
	v_fma_f32 v72, v36, v55, v70
	v_fma_f32 v73, v37, v54, v71
	v_cvt_pk_bf16_f32 v74, v72, v73
	v_fma_f32 v82, v18, v78, v222
	v_fma_f32 v83, v19, v79, v223
	v_fma_f32 v70, v56, v72, v125
	v_fma_f32 v71, v56, v73, v231
	v_mul_f32_e32 v84, 0x3d372713, v80
	v_mul_f32_e32 v85, 0x3d372713, v81
	v_fma_f32 v54, v36, v73, v70
	v_fma_f32 v55, v37, v72, v71
	v_cvt_pk_bf16_f32 v75, v54, v55
	v_mul_f32_e32 v86, 0x3d372713, v82
	v_mul_f32_e32 v87, 0x3d372713, v83
	ds_write2_b32 v243, v74, v75 offset0:0 offset1:68
	v_mfma_f32_32x32x16_bf16 v[88:103], v[200:203], v[42:45], v[88:103]
	v_mfma_f32_32x32x16_bf16 v[104:119], v[200:203], v[50:53], v[104:119]
	v_fma_f32 v70, v56, v54, v126
	v_fma_f32 v71, v56, v55, v232
	v_mul_f32_e32 v84, v80, v84
	v_mul_f32_e32 v85, v81, v85
	v_fma_f32 v72, v36, v55, v70
	v_fma_f32 v73, v37, v54, v71
	v_cvt_pk_bf16_f32 v74, v72, v73
	v_mul_f32_e32 v86, v82, v86
	v_mul_f32_e32 v87, v83, v87
	v_fma_f32 v70, v56, v72, v127
	v_fma_f32 v71, v56, v73, v233
	v_fma_f32 v84, v80, v84, v80
	v_fma_f32 v85, v81, v85, v81
	v_fma_f32 v54, v36, v73, v70
	v_fma_f32 v55, v37, v72, v71
	v_cvt_pk_bf16_f32 v75, v54, v55
	v_fma_f32 v86, v82, v86, v82
	v_fma_f32 v87, v83, v87, v83
	ds_write2_b32 v243, v74, v75 offset0:136 offset1:204
	v_fma_f32 v70, v56, v54, v128
	v_fma_f32 v71, v56, v55, v234
	v_mul_f32_e32 v84, 0x3fcc422a, v84
	v_mul_f32_e32 v85, 0x3fcc422a, v85
	v_fma_f32 v72, v36, v55, v70
	v_fma_f32 v73, v37, v54, v71
	v_cvt_pk_bf16_f32 v74, v72, v73
	v_mul_f32_e32 v86, 0x3fcc422a, v86
	v_mul_f32_e32 v87, 0x3fcc422a, v87
	v_fma_f32 v70, v56, v72, v129
	v_fma_f32 v71, v56, v73, v235
	v_mul_f32_e32 v84, 0xbfb8aa3b, v84
	v_mul_f32_e32 v85, 0xbfb8aa3b, v85
	v_fma_f32 v54, v36, v73, v70
	v_fma_f32 v55, v37, v72, v71
	v_cvt_pk_bf16_f32 v75, v54, v55
	v_mul_f32_e32 v86, 0xbfb8aa3b, v86
	ds_write2_b32 v244, v74, v75 offset0:0 offset1:68
	v_fma_f32 v70, v56, v54, v130
	v_fma_f32 v71, v56, v55, v236
	v_mul_f32_e32 v87, 0xbfb8aa3b, v87
	v_exp_f32_e32 v84, v84
	v_fma_f32 v72, v36, v55, v70
	v_fma_f32 v73, v37, v54, v71
	v_cvt_pk_bf16_f32 v74, v72, v73
	v_exp_f32_e32 v85, v85
	v_exp_f32_e32 v86, v86
	v_fma_f32 v70, v56, v72, v131
	v_fma_f32 v71, v56, v73, v237
	v_exp_f32_e32 v87, v87
	v_add_f32_e32 v84, 1.0, v84
	v_fma_f32 v54, v36, v73, v70
	v_fma_f32 v55, v37, v72, v71
	v_cvt_pk_bf16_f32 v75, v54, v55
	v_add_f32_e32 v85, 1.0, v85
	ds_write2_b32 v244, v74, v75 offset0:136 offset1:204
	v_fma_f32 v70, v56, v54, v132
	v_fma_f32 v71, v56, v55, v238
	v_add_f32_e32 v86, 1.0, v86
	v_add_f32_e32 v87, 1.0, v87
	v_fma_f32 v72, v36, v55, v70
	v_fma_f32 v73, v37, v54, v71
	v_cvt_pk_bf16_f32 v74, v72, v73
	v_rcp_f32_e32 v84, v84
	v_rcp_f32_e32 v85, v85
	v_fma_f32 v70, v56, v72, v133
	v_fma_f32 v71, v56, v73, v239
	v_rcp_f32_e32 v86, v86
	v_rcp_f32_e32 v87, v87
	v_fma_f32 v54, v36, v73, v70
	v_fma_f32 v55, v37, v72, v71
	v_cvt_pk_bf16_f32 v75, v54, v55
	s_nop 0
	ds_write2_b32 v245, v74, v75 offset0:0 offset1:68
	v_fma_f32 v70, v56, v54, v134
	v_fma_f32 v71, v56, v55, v240
	v_mul_f32_e32 v84, v80, v84
	v_mul_f32_e32 v85, v81, v85
	v_fma_f32 v72, v36, v55, v70
	v_fma_f32 v73, v37, v54, v71
	v_cvt_pk_bf16_f32 v74, v72, v73
	v_mul_f32_e32 v86, v82, v86
	v_mul_f32_e32 v87, v83, v87
	v_fma_f32 v70, v56, v72, v135
	v_fma_f32 v71, v56, v73, v241
	v_cvt_pk_bf16_f32 v84, v84, v85
	v_fma_f32 v54, v36, v73, v70
	v_fma_f32 v55, v37, v72, v71
	v_cvt_pk_bf16_f32 v75, v54, v55
	v_cvt_pk_bf16_f32 v85, v86, v87
	ds_write2_b32 v245, v74, v75 offset0:136 offset1:204
	global_store_dwordx2 v[246:247], v[84:85], off
	s_mov_b64 s[18:19], 0x4000
	v_lshl_add_u64 v[246:247], v[246:247], 0, s[18:19]
	s_mov_b64 s[18:19], 0x8000
	s_waitcnt vmcnt(9)
	ds_write_b64 v146, v[142:143]
	ds_read_b128 v[192:195], v69 offset:8448
	ds_read_b128 v[204:207], v69 offset:8512
	ds_read_b128 v[212:215], v69 offset:8576
	ds_read_b128 v[216:219], v69 offset:8640
	ds_read_b128 v[156:159], v196
	ds_read_b128 v[200:203], v197
	global_load_dwordx2 v[136:137], v[60:61], off
	v_lshl_add_u64 v[60:61], v[60:61], 0, s[18:19]
	v_fma_f32 v70, v56, v54, v88
	v_fma_f32 v71, v56, v55, v104
	v_lshlrev_b32_e32 v76, 16, v138
	v_fma_f32 v72, v36, v55, v70
	v_fma_f32 v73, v37, v54, v71
	v_cvt_pk_bf16_f32 v74, v72, v73
	v_and_b32_e32 v77, 0xffff0000, v138
	v_fma_f32 v70, v56, v72, v89
	v_fma_f32 v71, v56, v73, v105
	v_lshlrev_b32_e32 v78, 16, v139
	v_fma_f32 v54, v36, v73, v70
	v_fma_f32 v55, v37, v72, v71
	v_cvt_pk_bf16_f32 v75, v54, v55
	v_and_b32_e32 v79, 0xffff0000, v139
	ds_write2_b32 v242, v74, v75 offset0:0 offset1:68
	s_waitcnt lgkmcnt(3)
	v_mfma_f32_16x16x32_bf16 v[220:223], v[0:3], v[192:195], 0
	v_mfma_f32_16x16x32_bf16 v[220:223], v[4:7], v[204:207], v[220:223]
	v_mfma_f32_16x16x32_bf16 v[220:223], v[8:11], v[212:215], v[220:223]
	v_mfma_f32_16x16x32_bf16 v[220:223], v[12:15], v[216:219], v[220:223]
	v_fma_f32 v70, v56, v54, v90
	v_fma_f32 v71, v56, v55, v106
	v_fma_f32 v72, v36, v55, v70
	v_fma_f32 v73, v37, v54, v71
	v_cvt_pk_bf16_f32 v74, v72, v73
	v_fma_f32 v70, v56, v72, v91
	v_fma_f32 v71, v56, v73, v107
	v_fma_f32 v54, v36, v73, v70
	v_fma_f32 v55, v37, v72, v71
	v_cvt_pk_bf16_f32 v75, v54, v55
	ds_write2_b32 v242, v74, v75 offset0:136 offset1:204
	s_waitcnt lgkmcnt(2)
; #define LAS __attribute__((address_space(3)))
; __device__ __forceinline__ unsigned cvt_pk_bf16(float lo, float hi) { const f32x2 v = {lo, hi}; return __builtin_bit_cast(unsigned, __builtin_convertvector(v, bfx2_t)); }
; template <int PASS> __device__ void ssm_pass(const Params& P, int l, LAS unsigned char* lds) {
;     ...
;         for (int mt = 0; mt < 64; ++mt) {
;             u32x2 unext = ucur; if (mt < 63) unext = *(const u32x2*)(zrow + (size_t)(mt + 1) * 16 * DM);
;             const bf16x4 af = __builtin_bit_cast(bf16x4, ucur);
;             f32x4 d[8];
; #pragma unroll
;             for (int t = 0; t < 8; ++t) d[t] = __builtin_amdgcn_mfma_f32_16x16x16bf16_1k(af, bf[t], (f32x4){0.f, 0.f, 0.f, 0.f}, 0, 0, 0);
; #pragma unroll
;             for (int tq = 0; tq < 4; ++tq)
; #pragma unroll
;                 for (int j = 0; j < 4; ++j) *(LAS f32x2*)(BU + (4 * fq + j) * 528 + (16 * tq + fr) * 8) = (f32x2){d[tq][j], d[tq + 4][j]};
;             asm volatile("s_waitcnt lgkmcnt(0)" ::: "memory");
; #pragma unroll
;             for (int j = 0; j < 16; ++j) {
;                 const f32x2 bu = *(const LAS f32x2*)(BU + j * 528 + lane * 8);
;                 sv = __builtin_elementwise_fma(ayn, __builtin_shufflevector(sv, sv, 1, 0), __builtin_elementwise_fma(axx, sv, bu));
;                 if (PASS == 2) *(LAS unsigned*)(SI + j * 272 + lane * 4) = cvt_pk_bf16(sv.x, sv.y);
;             }
;             if (PASS == 2) {
;                 asm volatile("s_waitcnt lgkmcnt(0)" ::: "memory");
;                 f32x4 acc = (f32x4){0.f, 0.f, 0.f, 0.f};
; #pragma unroll
;                 for (int kt = 0; kt < 4; ++kt) { const bf16x8 sv = *(const LAS bf16x8*)(SI + fr * 272 + (32 * kt + 8 * fq) * 2);
;                     acc = __builtin_amdgcn_mfma_f32_16x16x32_bf16(cf[kt], sv, acc, 0, 0, 0); }
;                 const size_t tok = tok0 + 16 * mt + fr;
;                 float o[4];
;                 const float uf[4] = {bflo(ucur.x), bfhi(ucur.x), bflo(ucur.y), bfhi(ucur.y)};
; #pragma unroll
;                 for (int j = 0; j < 4; ++j) { const float y = acc[j] + dd[j] * uf[j]; o[j] = y * fsigmoid(1.5957691216057308f * (y + 0.044715f * y * y * y)); }
;                 u32x2 w; w.x = cvt_pk_bf16(o[0], o[1]); w.y = cvt_pk_bf16(o[2], o[3]);
;                 *(u32x2*)(ypre + tok * 512 + g * 16 + 4 * fq) = w;
	v_mfma_f32_32x32x16_bf16 v[120:135], v[156:159], v[38:41], 0
	v_mfma_f32_32x32x16_bf16 v[226:241], v[156:159], v[46:49], 0
	v_fma_f32 v70, v56, v54, v92
	v_fma_f32 v71, v56, v55, v108
	v_fma_f32 v80, v16, v76, v220
	v_fma_f32 v81, v17, v77, v221
	v_fma_f32 v72, v36, v55, v70
	v_fma_f32 v73, v37, v54, v71
	v_cvt_pk_bf16_f32 v74, v72, v73
	v_fma_f32 v82, v18, v78, v222
	v_fma_f32 v83, v19, v79, v223
	v_fma_f32 v70, v56, v72, v93
	v_fma_f32 v71, v56, v73, v109
	v_mul_f32_e32 v84, 0x3d372713, v80
	v_mul_f32_e32 v85, 0x3d372713, v81
	v_fma_f32 v54, v36, v73, v70
	v_fma_f32 v55, v37, v72, v71
	v_cvt_pk_bf16_f32 v75, v54, v55
	v_mul_f32_e32 v86, 0x3d372713, v82
	v_mul_f32_e32 v87, 0x3d372713, v83
	ds_write2_b32 v243, v74, v75 offset0:0 offset1:68
	v_mfma_f32_32x32x16_bf16 v[120:135], v[200:203], v[42:45], v[120:135]
	v_mfma_f32_32x32x16_bf16 v[226:241], v[200:203], v[50:53], v[226:241]
	v_fma_f32 v70, v56, v54, v94
	v_fma_f32 v71, v56, v55, v110
	v_mul_f32_e32 v84, v80, v84
	v_mul_f32_e32 v85, v81, v85
	v_fma_f32 v72, v36, v55, v70
	v_fma_f32 v73, v37, v54, v71
	v_cvt_pk_bf16_f32 v74, v72, v73
	v_mul_f32_e32 v86, v82, v86
	v_mul_f32_e32 v87, v83, v87
	v_fma_f32 v70, v56, v72, v95
	v_fma_f32 v71, v56, v73, v111
	v_fma_f32 v84, v80, v84, v80
	v_fma_f32 v85, v81, v85, v81
	v_fma_f32 v54, v36, v73, v70
	v_fma_f32 v55, v37, v72, v71
	v_cvt_pk_bf16_f32 v75, v54, v55
	v_fma_f32 v86, v82, v86, v82
	v_fma_f32 v87, v83, v87, v83
	ds_write2_b32 v243, v74, v75 offset0:136 offset1:204
	v_fma_f32 v70, v56, v54, v96
	v_fma_f32 v71, v56, v55, v112
	v_mul_f32_e32 v84, 0x3fcc422a, v84
	v_mul_f32_e32 v85, 0x3fcc422a, v85
	v_fma_f32 v72, v36, v55, v70
	v_fma_f32 v73, v37, v54, v71
	v_cvt_pk_bf16_f32 v74, v72, v73
	v_mul_f32_e32 v86, 0x3fcc422a, v86
	v_mul_f32_e32 v87, 0x3fcc422a, v87
	v_fma_f32 v70, v56, v72, v97
	v_fma_f32 v71, v56, v73, v113
	v_mul_f32_e32 v84, 0xbfb8aa3b, v84
	v_mul_f32_e32 v85, 0xbfb8aa3b, v85
	v_fma_f32 v54, v36, v73, v70
	v_fma_f32 v55, v37, v72, v71
	v_cvt_pk_bf16_f32 v75, v54, v55
	v_mul_f32_e32 v86, 0xbfb8aa3b, v86
	ds_write2_b32 v244, v74, v75 offset0:0 offset1:68
	v_fma_f32 v70, v56, v54, v98
	v_fma_f32 v71, v56, v55, v114
	v_mul_f32_e32 v87, 0xbfb8aa3b, v87
	v_exp_f32_e32 v84, v84
	v_fma_f32 v72, v36, v55, v70
	v_fma_f32 v73, v37, v54, v71
	v_cvt_pk_bf16_f32 v74, v72, v73
	v_exp_f32_e32 v85, v85
	v_exp_f32_e32 v86, v86
	v_fma_f32 v70, v56, v72, v99
	v_fma_f32 v71, v56, v73, v115
	v_exp_f32_e32 v87, v87
	v_add_f32_e32 v84, 1.0, v84
	v_fma_f32 v54, v36, v73, v70
	v_fma_f32 v55, v37, v72, v71
	v_cvt_pk_bf16_f32 v75, v54, v55
	v_add_f32_e32 v85, 1.0, v85
	ds_write2_b32 v244, v74, v75 offset0:136 offset1:204
	v_fma_f32 v70, v56, v54, v100
	v_fma_f32 v71, v56, v55, v116
	v_add_f32_e32 v86, 1.0, v86
	v_add_f32_e32 v87, 1.0, v87
	v_fma_f32 v72, v36, v55, v70
	v_fma_f32 v73, v37, v54, v71
	v_cvt_pk_bf16_f32 v74, v72, v73
	v_rcp_f32_e32 v84, v84
	v_rcp_f32_e32 v85, v85
	v_fma_f32 v70, v56, v72, v101
	v_fma_f32 v71, v56, v73, v117
	v_rcp_f32_e32 v86, v86
	v_rcp_f32_e32 v87, v87
	v_fma_f32 v54, v36, v73, v70
	v_fma_f32 v55, v37, v72, v71
	v_cvt_pk_bf16_f32 v75, v54, v55
	s_nop 0
	ds_write2_b32 v245, v74, v75 offset0:0 offset1:68
	v_fma_f32 v70, v56, v54, v102
	v_fma_f32 v71, v56, v55, v118
	v_mul_f32_e32 v84, v80, v84
	v_mul_f32_e32 v85, v81, v85
	v_fma_f32 v72, v36, v55, v70
	v_fma_f32 v73, v37, v54, v71
	v_cvt_pk_bf16_f32 v74, v72, v73
	v_mul_f32_e32 v86, v82, v86
	v_mul_f32_e32 v87, v83, v87
	v_fma_f32 v70, v56, v72, v103
	v_fma_f32 v71, v56, v73, v119
	v_cvt_pk_bf16_f32 v84, v84, v85
	v_fma_f32 v54, v36, v73, v70
	v_fma_f32 v55, v37, v72, v71
	v_cvt_pk_bf16_f32 v75, v54, v55
	v_cvt_pk_bf16_f32 v85, v86, v87
	ds_write2_b32 v245, v74, v75 offset0:136 offset1:204
	global_store_dwordx2 v[246:247], v[84:85], off
	s_mov_b64 s[18:19], 0x4000
	v_lshl_add_u64 v[246:247], v[246:247], 0, s[18:19]
	s_mov_b64 s[18:19], 0x8000
	s_waitcnt vmcnt(9)
	ds_write_b64 v146, v[144:145]
	ds_read_b128 v[192:195], v69 offset:8448
	ds_read_b128 v[204:207], v69 offset:8512
	ds_read_b128 v[212:215], v69 offset:8576
	ds_read_b128 v[216:219], v69 offset:8640
	ds_read_b128 v[156:159], v196
	ds_read_b128 v[200:203], v197
	global_load_dwordx2 v[138:139], v[60:61], off
	v_lshl_add_u64 v[60:61], v[60:61], 0, s[18:19]
	v_fma_f32 v70, v56, v54, v120
	v_fma_f32 v71, v56, v55, v226
	v_lshlrev_b32_e32 v76, 16, v140
	v_fma_f32 v72, v36, v55, v70
	v_fma_f32 v73, v37, v54, v71
	v_cvt_pk_bf16_f32 v74, v72, v73
	v_and_b32_e32 v77, 0xffff0000, v140
	v_fma_f32 v70, v56, v72, v121
	v_fma_f32 v71, v56, v73, v227
	v_lshlrev_b32_e32 v78, 16, v141
	v_fma_f32 v54, v36, v73, v70
	v_fma_f32 v55, v37, v72, v71
	v_cvt_pk_bf16_f32 v75, v54, v55
	v_and_b32_e32 v79, 0xffff0000, v141
	ds_write2_b32 v242, v74, v75 offset0:0 offset1:68
	s_waitcnt lgkmcnt(3)
	v_mfma_f32_16x16x32_bf16 v[220:223], v[0:3], v[192:195], 0
	v_mfma_f32_16x16x32_bf16 v[220:223], v[4:7], v[204:207], v[220:223]
	v_mfma_f32_16x16x32_bf16 v[220:223], v[8:11], v[212:215], v[220:223]
	v_mfma_f32_16x16x32_bf16 v[220:223], v[12:15], v[216:219], v[220:223]
	v_fma_f32 v70, v56, v54, v122
	v_fma_f32 v71, v56, v55, v228
	v_fma_f32 v72, v36, v55, v70
	v_fma_f32 v73, v37, v54, v71
	v_cvt_pk_bf16_f32 v74, v72, v73
	v_fma_f32 v70, v56, v72, v123
	v_fma_f32 v71, v56, v73, v229
	v_fma_f32 v54, v36, v73, v70
	v_fma_f32 v55, v37, v72, v71
	v_cvt_pk_bf16_f32 v75, v54, v55
	ds_write2_b32 v242, v74, v75 offset0:136 offset1:204
	s_waitcnt lgkmcnt(2)
; #define LAS __attribute__((address_space(3)))
; __device__ __forceinline__ unsigned cvt_pk_bf16(float lo, float hi) { const f32x2 v = {lo, hi}; return __builtin_bit_cast(unsigned, __builtin_convertvector(v, bfx2_t)); }
; template <int PASS> __device__ void ssm_pass(const Params& P, int l, LAS unsigned char* lds) {
;     ...
;         for (int mt = 0; mt < 64; ++mt) {
;             u32x2 unext = ucur; if (mt < 63) unext = *(const u32x2*)(zrow + (size_t)(mt + 1) * 16 * DM);
;             const bf16x4 af = __builtin_bit_cast(bf16x4, ucur);
;             f32x4 d[8];
; #pragma unroll
;             for (int t = 0; t < 8; ++t) d[t] = __builtin_amdgcn_mfma_f32_16x16x16bf16_1k(af, bf[t], (f32x4){0.f, 0.f, 0.f, 0.f}, 0, 0, 0);
; #pragma unroll
;             for (int tq = 0; tq < 4; ++tq)
; #pragma unroll
;                 for (int j = 0; j < 4; ++j) *(LAS f32x2*)(BU + (4 * fq + j) * 528 + (16 * tq + fr) * 8) = (f32x2){d[tq][j], d[tq + 4][j]};
;             asm volatile("s_waitcnt lgkmcnt(0)" ::: "memory");
; #pragma unroll
;             for (int j = 0; j < 16; ++j) {
;                 const f32x2 bu = *(const LAS f32x2*)(BU + j * 528 + lane * 8);
;                 sv = __builtin_elementwise_fma(ayn, __builtin_shufflevector(sv, sv, 1, 0), __builtin_elementwise_fma(axx, sv, bu));
;                 if (PASS == 2) *(LAS unsigned*)(SI + j * 272 + lane * 4) = cvt_pk_bf16(sv.x, sv.y);
;             }
;             if (PASS == 2) {
;                 asm volatile("s_waitcnt lgkmcnt(0)" ::: "memory");
;                 f32x4 acc = (f32x4){0.f, 0.f, 0.f, 0.f};
; #pragma unroll
;                 for (int kt = 0; kt < 4; ++kt) { const bf16x8 sv = *(const LAS bf16x8*)(SI + fr * 272 + (32 * kt + 8 * fq) * 2);
;                     acc = __builtin_amdgcn_mfma_f32_16x16x32_bf16(cf[kt], sv, acc, 0, 0, 0); }
;                 const size_t tok = tok0 + 16 * mt + fr;
;                 float o[4];
;                 const float uf[4] = {bflo(ucur.x), bfhi(ucur.x), bflo(ucur.y), bfhi(ucur.y)};
; #pragma unroll
;                 for (int j = 0; j < 4; ++j) { const float y = acc[j] + dd[j] * uf[j]; o[j] = y * fsigmoid(1.5957691216057308f * (y + 0.044715f * y * y * y)); }
;                 u32x2 w; w.x = cvt_pk_bf16(o[0], o[1]); w.y = cvt_pk_bf16(o[2], o[3]);
;                 *(u32x2*)(ypre + tok * 512 + g * 16 + 4 * fq) = w;
	v_mfma_f32_32x32x16_bf16 v[88:103], v[156:159], v[38:41], 0
	v_mfma_f32_32x32x16_bf16 v[104:119], v[156:159], v[46:49], 0
	v_fma_f32 v70, v56, v54, v124
	v_fma_f32 v71, v56, v55, v230
	v_fma_f32 v80, v16, v76, v220
	v_fma_f32 v81, v17, v77, v221
	v_fma_f32 v72, v36, v55, v70
	v_fma_f32 v73, v37, v54, v71
	v_cvt_pk_bf16_f32 v74, v72, v73
	v_fma_f32 v82, v18, v78, v222
	v_fma_f32 v83, v19, v79, v223
	v_fma_f32 v70, v56, v72, v125
	v_fma_f32 v71, v56, v73, v231
	v_mul_f32_e32 v84, 0x3d372713, v80
	v_mul_f32_e32 v85, 0x3d372713, v81
	v_fma_f32 v54, v36, v73, v70
	v_fma_f32 v55, v37, v72, v71
	v_cvt_pk_bf16_f32 v75, v54, v55
	v_mul_f32_e32 v86, 0x3d372713, v82
	v_mul_f32_e32 v87, 0x3d372713, v83
	ds_write2_b32 v243, v74, v75 offset0:0 offset1:68
	v_mfma_f32_32x32x16_bf16 v[88:103], v[200:203], v[42:45], v[88:103]
	v_mfma_f32_32x32x16_bf16 v[104:119], v[200:203], v[50:53], v[104:119]
	v_fma_f32 v70, v56, v54, v126
	v_fma_f32 v71, v56, v55, v232
	v_mul_f32_e32 v84, v80, v84
	v_mul_f32_e32 v85, v81, v85
	v_fma_f32 v72, v36, v55, v70
	v_fma_f32 v73, v37, v54, v71
	v_cvt_pk_bf16_f32 v74, v72, v73
	v_mul_f32_e32 v86, v82, v86
	v_mul_f32_e32 v87, v83, v87
	v_fma_f32 v70, v56, v72, v127
	v_fma_f32 v71, v56, v73, v233
	v_fma_f32 v84, v80, v84, v80
	v_fma_f32 v85, v81, v85, v81
	v_fma_f32 v54, v36, v73, v70
	v_fma_f32 v55, v37, v72, v71
	v_cvt_pk_bf16_f32 v75, v54, v55
	v_fma_f32 v86, v82, v86, v82
	v_fma_f32 v87, v83, v87, v83
	ds_write2_b32 v243, v74, v75 offset0:136 offset1:204
	v_fma_f32 v70, v56, v54, v128
	v_fma_f32 v71, v56, v55, v234
	v_mul_f32_e32 v84, 0x3fcc422a, v84
	v_mul_f32_e32 v85, 0x3fcc422a, v85
	v_fma_f32 v72, v36, v55, v70
	v_fma_f32 v73, v37, v54, v71
	v_cvt_pk_bf16_f32 v74, v72, v73
	v_mul_f32_e32 v86, 0x3fcc422a, v86
	v_mul_f32_e32 v87, 0x3fcc422a, v87
	v_fma_f32 v70, v56, v72, v129
	v_fma_f32 v71, v56, v73, v235
	v_mul_f32_e32 v84, 0xbfb8aa3b, v84
	v_mul_f32_e32 v85, 0xbfb8aa3b, v85
	v_fma_f32 v54, v36, v73, v70
	v_fma_f32 v55, v37, v72, v71
	v_cvt_pk_bf16_f32 v75, v54, v55
	v_mul_f32_e32 v86, 0xbfb8aa3b, v86
	ds_write2_b32 v244, v74, v75 offset0:0 offset1:68
	v_fma_f32 v70, v56, v54, v130
	v_fma_f32 v71, v56, v55, v236
	v_mul_f32_e32 v87, 0xbfb8aa3b, v87
	v_exp_f32_e32 v84, v84
	v_fma_f32 v72, v36, v55, v70
	v_fma_f32 v73, v37, v54, v71
	v_cvt_pk_bf16_f32 v74, v72, v73
	v_exp_f32_e32 v85, v85
	v_exp_f32_e32 v86, v86
	v_fma_f32 v70, v56, v72, v131
	v_fma_f32 v71, v56, v73, v237
	v_exp_f32_e32 v87, v87
	v_add_f32_e32 v84, 1.0, v84
	v_fma_f32 v54, v36, v73, v70
	v_fma_f32 v55, v37, v72, v71
	v_cvt_pk_bf16_f32 v75, v54, v55
	v_add_f32_e32 v85, 1.0, v85
	ds_write2_b32 v244, v74, v75 offset0:136 offset1:204
	v_fma_f32 v70, v56, v54, v132
	v_fma_f32 v71, v56, v55, v238
	v_add_f32_e32 v86, 1.0, v86
	v_add_f32_e32 v87, 1.0, v87
	v_fma_f32 v72, v36, v55, v70
	v_fma_f32 v73, v37, v54, v71
	v_cvt_pk_bf16_f32 v74, v72, v73
	v_rcp_f32_e32 v84, v84
	v_rcp_f32_e32 v85, v85
	v_fma_f32 v70, v56, v72, v133
	v_fma_f32 v71, v56, v73, v239
	v_rcp_f32_e32 v86, v86
	v_rcp_f32_e32 v87, v87
	v_fma_f32 v54, v36, v73, v70
	v_fma_f32 v55, v37, v72, v71
	v_cvt_pk_bf16_f32 v75, v54, v55
	s_nop 0
	ds_write2_b32 v245, v74, v75 offset0:0 offset1:68
	v_fma_f32 v70, v56, v54, v134
	v_fma_f32 v71, v56, v55, v240
	v_mul_f32_e32 v84, v80, v84
	v_mul_f32_e32 v85, v81, v85
	v_fma_f32 v72, v36, v55, v70
	v_fma_f32 v73, v37, v54, v71
	v_cvt_pk_bf16_f32 v74, v72, v73
	v_mul_f32_e32 v86, v82, v86
	v_mul_f32_e32 v87, v83, v87
	v_fma_f32 v70, v56, v72, v135
	v_fma_f32 v71, v56, v73, v241
	v_cvt_pk_bf16_f32 v84, v84, v85
	v_fma_f32 v54, v36, v73, v70
	v_fma_f32 v55, v37, v72, v71
	v_cvt_pk_bf16_f32 v75, v54, v55
	v_cvt_pk_bf16_f32 v85, v86, v87
	ds_write2_b32 v245, v74, v75 offset0:136 offset1:204
	global_store_dwordx2 v[246:247], v[84:85], off
	s_mov_b64 s[18:19], 0x4000
	v_lshl_add_u64 v[246:247], v[246:247], 0, s[18:19]
	s_mov_b64 s[18:19], 0x8000
	s_waitcnt vmcnt(9)
	ds_write_b64 v146, v[148:149]
	ds_read_b128 v[192:195], v69 offset:8448
	ds_read_b128 v[204:207], v69 offset:8512
	ds_read_b128 v[212:215], v69 offset:8576
	ds_read_b128 v[216:219], v69 offset:8640
	ds_read_b128 v[156:159], v196
	ds_read_b128 v[200:203], v197
	global_load_dwordx2 v[140:141], v[60:61], off
	v_lshl_add_u64 v[60:61], v[60:61], 0, s[18:19]
	v_fma_f32 v70, v56, v54, v88
	v_fma_f32 v71, v56, v55, v104
	v_lshlrev_b32_e32 v76, 16, v142
	v_fma_f32 v72, v36, v55, v70
	v_fma_f32 v73, v37, v54, v71
	v_cvt_pk_bf16_f32 v74, v72, v73
	v_and_b32_e32 v77, 0xffff0000, v142
	v_fma_f32 v70, v56, v72, v89
	v_fma_f32 v71, v56, v73, v105
	v_lshlrev_b32_e32 v78, 16, v143
	v_fma_f32 v54, v36, v73, v70
	v_fma_f32 v55, v37, v72, v71
	v_cvt_pk_bf16_f32 v75, v54, v55
	v_and_b32_e32 v79, 0xffff0000, v143
	ds_write2_b32 v242, v74, v75 offset0:0 offset1:68
	s_waitcnt lgkmcnt(3)
	v_mfma_f32_16x16x32_bf16 v[220:223], v[0:3], v[192:195], 0
	v_mfma_f32_16x16x32_bf16 v[220:223], v[4:7], v[204:207], v[220:223]
	v_mfma_f32_16x16x32_bf16 v[220:223], v[8:11], v[212:215], v[220:223]
	v_mfma_f32_16x16x32_bf16 v[220:223], v[12:15], v[216:219], v[220:223]
	v_fma_f32 v70, v56, v54, v90
	v_fma_f32 v71, v56, v55, v106
	v_fma_f32 v72, v36, v55, v70
	v_fma_f32 v73, v37, v54, v71
	v_cvt_pk_bf16_f32 v74, v72, v73
	v_fma_f32 v70, v56, v72, v91
	v_fma_f32 v71, v56, v73, v107
	v_fma_f32 v54, v36, v73, v70
	v_fma_f32 v55, v37, v72, v71
	v_cvt_pk_bf16_f32 v75, v54, v55
	ds_write2_b32 v242, v74, v75 offset0:136 offset1:204
	s_waitcnt lgkmcnt(2)
; #define LAS __attribute__((address_space(3)))
; __device__ __forceinline__ unsigned cvt_pk_bf16(float lo, float hi) { const f32x2 v = {lo, hi}; return __builtin_bit_cast(unsigned, __builtin_convertvector(v, bfx2_t)); }
; template <int PASS> __device__ void ssm_pass(const Params& P, int l, LAS unsigned char* lds) {
;     ...
;         for (int mt = 0; mt < 64; ++mt) {
;             u32x2 unext = ucur; if (mt < 63) unext = *(const u32x2*)(zrow + (size_t)(mt + 1) * 16 * DM);
;             const bf16x4 af = __builtin_bit_cast(bf16x4, ucur);
;             f32x4 d[8];
; #pragma unroll
;             for (int t = 0; t < 8; ++t) d[t] = __builtin_amdgcn_mfma_f32_16x16x16bf16_1k(af, bf[t], (f32x4){0.f, 0.f, 0.f, 0.f}, 0, 0, 0);
; #pragma unroll
;             for (int tq = 0; tq < 4; ++tq)
; #pragma unroll
;                 for (int j = 0; j < 4; ++j) *(LAS f32x2*)(BU + (4 * fq + j) * 528 + (16 * tq + fr) * 8) = (f32x2){d[tq][j], d[tq + 4][j]};
;             asm volatile("s_waitcnt lgkmcnt(0)" ::: "memory");
; #pragma unroll
;             for (int j = 0; j < 16; ++j) {
;                 const f32x2 bu = *(const LAS f32x2*)(BU + j * 528 + lane * 8);
;                 sv = __builtin_elementwise_fma(ayn, __builtin_shufflevector(sv, sv, 1, 0), __builtin_elementwise_fma(axx, sv, bu));
;                 if (PASS == 2) *(LAS unsigned*)(SI + j * 272 + lane * 4) = cvt_pk_bf16(sv.x, sv.y);
;             }
;             if (PASS == 2) {
;                 asm volatile("s_waitcnt lgkmcnt(0)" ::: "memory");
;                 f32x4 acc = (f32x4){0.f, 0.f, 0.f, 0.f};
; #pragma unroll
;                 for (int kt = 0; kt < 4; ++kt) { const bf16x8 sv = *(const LAS bf16x8*)(SI + fr * 272 + (32 * kt + 8 * fq) * 2);
;                     acc = __builtin_amdgcn_mfma_f32_16x16x32_bf16(cf[kt], sv, acc, 0, 0, 0); }
;                 const size_t tok = tok0 + 16 * mt + fr;
;                 float o[4];
;                 const float uf[4] = {bflo(ucur.x), bfhi(ucur.x), bflo(ucur.y), bfhi(ucur.y)};
; #pragma unroll
;                 for (int j = 0; j < 4; ++j) { const float y = acc[j] + dd[j] * uf[j]; o[j] = y * fsigmoid(1.5957691216057308f * (y + 0.044715f * y * y * y)); }
;                 u32x2 w; w.x = cvt_pk_bf16(o[0], o[1]); w.y = cvt_pk_bf16(o[2], o[3]);
;                 *(u32x2*)(ypre + tok * 512 + g * 16 + 4 * fq) = w;
	v_mfma_f32_32x32x16_bf16 v[120:135], v[156:159], v[38:41], 0
	v_mfma_f32_32x32x16_bf16 v[226:241], v[156:159], v[46:49], 0
	v_fma_f32 v70, v56, v54, v92
	v_fma_f32 v71, v56, v55, v108
	v_fma_f32 v80, v16, v76, v220
	v_fma_f32 v81, v17, v77, v221
	v_fma_f32 v72, v36, v55, v70
	v_fma_f32 v73, v37, v54, v71
	v_cvt_pk_bf16_f32 v74, v72, v73
	v_fma_f32 v82, v18, v78, v222
	v_fma_f32 v83, v19, v79, v223
	v_fma_f32 v70, v56, v72, v93
	v_fma_f32 v71, v56, v73, v109
	v_mul_f32_e32 v84, 0x3d372713, v80
	v_mul_f32_e32 v85, 0x3d372713, v81
	v_fma_f32 v54, v36, v73, v70
	v_fma_f32 v55, v37, v72, v71
	v_cvt_pk_bf16_f32 v75, v54, v55
	v_mul_f32_e32 v86, 0x3d372713, v82
	v_mul_f32_e32 v87, 0x3d372713, v83
	ds_write2_b32 v243, v74, v75 offset0:0 offset1:68
	v_mfma_f32_32x32x16_bf16 v[120:135], v[200:203], v[42:45], v[120:135]
	v_mfma_f32_32x32x16_bf16 v[226:241], v[200:203], v[50:53], v[226:241]
	v_fma_f32 v70, v56, v54, v94
	v_fma_f32 v71, v56, v55, v110
	v_mul_f32_e32 v84, v80, v84
	v_mul_f32_e32 v85, v81, v85
	v_fma_f32 v72, v36, v55, v70
	v_fma_f32 v73, v37, v54, v71
	v_cvt_pk_bf16_f32 v74, v72, v73
	v_mul_f32_e32 v86, v82, v86
	v_mul_f32_e32 v87, v83, v87
	v_fma_f32 v70, v56, v72, v95
	v_fma_f32 v71, v56, v73, v111
	v_fma_f32 v84, v80, v84, v80
	v_fma_f32 v85, v81, v85, v81
	v_fma_f32 v54, v36, v73, v70
	v_fma_f32 v55, v37, v72, v71
	v_cvt_pk_bf16_f32 v75, v54, v55
	v_fma_f32 v86, v82, v86, v82
	v_fma_f32 v87, v83, v87, v83
	ds_write2_b32 v243, v74, v75 offset0:136 offset1:204
	v_fma_f32 v70, v56, v54, v96
	v_fma_f32 v71, v56, v55, v112
	v_mul_f32_e32 v84, 0x3fcc422a, v84
	v_mul_f32_e32 v85, 0x3fcc422a, v85
	v_fma_f32 v72, v36, v55, v70
	v_fma_f32 v73, v37, v54, v71
	v_cvt_pk_bf16_f32 v74, v72, v73
	v_mul_f32_e32 v86, 0x3fcc422a, v86
	v_mul_f32_e32 v87, 0x3fcc422a, v87
	v_fma_f32 v70, v56, v72, v97
	v_fma_f32 v71, v56, v73, v113
	v_mul_f32_e32 v84, 0xbfb8aa3b, v84
	v_mul_f32_e32 v85, 0xbfb8aa3b, v85
	v_fma_f32 v54, v36, v73, v70
	v_fma_f32 v55, v37, v72, v71
	v_cvt_pk_bf16_f32 v75, v54, v55
	v_mul_f32_e32 v86, 0xbfb8aa3b, v86
	ds_write2_b32 v244, v74, v75 offset0:0 offset1:68
	v_fma_f32 v70, v56, v54, v98
	v_fma_f32 v71, v56, v55, v114
	v_mul_f32_e32 v87, 0xbfb8aa3b, v87
	v_exp_f32_e32 v84, v84
	v_fma_f32 v72, v36, v55, v70
	v_fma_f32 v73, v37, v54, v71
	v_cvt_pk_bf16_f32 v74, v72, v73
	v_exp_f32_e32 v85, v85
	v_exp_f32_e32 v86, v86
	v_fma_f32 v70, v56, v72, v99
	v_fma_f32 v71, v56, v73, v115
	v_exp_f32_e32 v87, v87
	v_add_f32_e32 v84, 1.0, v84
	v_fma_f32 v54, v36, v73, v70
	v_fma_f32 v55, v37, v72, v71
	v_cvt_pk_bf16_f32 v75, v54, v55
	v_add_f32_e32 v85, 1.0, v85
	ds_write2_b32 v244, v74, v75 offset0:136 offset1:204
	v_fma_f32 v70, v56, v54, v100
	v_fma_f32 v71, v56, v55, v116
	v_add_f32_e32 v86, 1.0, v86
	v_add_f32_e32 v87, 1.0, v87
	v_fma_f32 v72, v36, v55, v70
	v_fma_f32 v73, v37, v54, v71
	v_cvt_pk_bf16_f32 v74, v72, v73
	v_rcp_f32_e32 v84, v84
	v_rcp_f32_e32 v85, v85
	v_fma_f32 v70, v56, v72, v101
	v_fma_f32 v71, v56, v73, v117
	v_rcp_f32_e32 v86, v86
	v_rcp_f32_e32 v87, v87
	v_fma_f32 v54, v36, v73, v70
	v_fma_f32 v55, v37, v72, v71
	v_cvt_pk_bf16_f32 v75, v54, v55
	s_nop 0
	ds_write2_b32 v245, v74, v75 offset0:0 offset1:68
	v_fma_f32 v70, v56, v54, v102
	v_fma_f32 v71, v56, v55, v118
	v_mul_f32_e32 v84, v80, v84
	v_mul_f32_e32 v85, v81, v85
	v_fma_f32 v72, v36, v55, v70
	v_fma_f32 v73, v37, v54, v71
	v_cvt_pk_bf16_f32 v74, v72, v73
	v_mul_f32_e32 v86, v82, v86
	v_mul_f32_e32 v87, v83, v87
	v_fma_f32 v70, v56, v72, v103
	v_fma_f32 v71, v56, v73, v119
	v_cvt_pk_bf16_f32 v84, v84, v85
	v_fma_f32 v54, v36, v73, v70
	v_fma_f32 v55, v37, v72, v71
	v_cvt_pk_bf16_f32 v75, v54, v55
	v_cvt_pk_bf16_f32 v85, v86, v87
	ds_write2_b32 v245, v74, v75 offset0:136 offset1:204
	global_store_dwordx2 v[246:247], v[84:85], off
	s_mov_b64 s[18:19], 0x4000
	v_lshl_add_u64 v[246:247], v[246:247], 0, s[18:19]
	s_mov_b64 s[18:19], 0x8000
	s_waitcnt vmcnt(9)
	ds_write_b64 v146, v[64:65]
	ds_read_b128 v[192:195], v69 offset:8448
	ds_read_b128 v[204:207], v69 offset:8512
	ds_read_b128 v[212:215], v69 offset:8576
	ds_read_b128 v[216:219], v69 offset:8640
	ds_read_b128 v[156:159], v196
	ds_read_b128 v[200:203], v197
	global_load_dwordx2 v[142:143], v[60:61], off
	v_lshl_add_u64 v[60:61], v[60:61], 0, s[18:19]
	v_fma_f32 v70, v56, v54, v120
	v_fma_f32 v71, v56, v55, v226
	v_lshlrev_b32_e32 v76, 16, v144
	v_fma_f32 v72, v36, v55, v70
	v_fma_f32 v73, v37, v54, v71
	v_cvt_pk_bf16_f32 v74, v72, v73
	v_and_b32_e32 v77, 0xffff0000, v144
	v_fma_f32 v70, v56, v72, v121
	v_fma_f32 v71, v56, v73, v227
	v_lshlrev_b32_e32 v78, 16, v145
	v_fma_f32 v54, v36, v73, v70
	v_fma_f32 v55, v37, v72, v71
	v_cvt_pk_bf16_f32 v75, v54, v55
	v_and_b32_e32 v79, 0xffff0000, v145
	ds_write2_b32 v242, v74, v75 offset0:0 offset1:68
	s_waitcnt lgkmcnt(3)
	v_mfma_f32_16x16x32_bf16 v[220:223], v[0:3], v[192:195], 0
	v_mfma_f32_16x16x32_bf16 v[220:223], v[4:7], v[204:207], v[220:223]
	v_mfma_f32_16x16x32_bf16 v[220:223], v[8:11], v[212:215], v[220:223]
	v_mfma_f32_16x16x32_bf16 v[220:223], v[12:15], v[216:219], v[220:223]
	v_fma_f32 v70, v56, v54, v122
	v_fma_f32 v71, v56, v55, v228
	v_fma_f32 v72, v36, v55, v70
	v_fma_f32 v73, v37, v54, v71
	v_cvt_pk_bf16_f32 v74, v72, v73
	v_fma_f32 v70, v56, v72, v123
	v_fma_f32 v71, v56, v73, v229
	v_fma_f32 v54, v36, v73, v70
	v_fma_f32 v55, v37, v72, v71
	v_cvt_pk_bf16_f32 v75, v54, v55
	ds_write2_b32 v242, v74, v75 offset0:136 offset1:204
	s_waitcnt lgkmcnt(2)
; #define LAS __attribute__((address_space(3)))
; __device__ __forceinline__ float bflo(unsigned w) { return __uint_as_float(w << 16); }
; template <int PASS> __device__ void ssm_pass(const Params& P, int l, LAS unsigned char* lds) {
;     ...
;         for (int mt = 0; mt < 64; ++mt) {
;             u32x2 unext = ucur; if (mt < 63) unext = *(const u32x2*)(zrow + (size_t)(mt + 1) * 16 * DM);
;             const bf16x4 af = __builtin_bit_cast(bf16x4, ucur);
;             f32x4 d[8];
; #pragma unroll
;             for (int t = 0; t < 8; ++t) d[t] = __builtin_amdgcn_mfma_f32_16x16x16bf16_1k(af, bf[t], (f32x4){0.f, 0.f, 0.f, 0.f}, 0, 0, 0);
; #pragma unroll
;             for (int tq = 0; tq < 4; ++tq)
; #pragma unroll
;                 for (int j = 0; j < 4; ++j) *(LAS f32x2*)(BU + (4 * fq + j) * 528 + (16 * tq + fr) * 8) = (f32x2){d[tq][j], d[tq + 4][j]};
;             asm volatile("s_waitcnt lgkmcnt(0)" ::: "memory");
; #pragma unroll
;             for (int j = 0; j < 16; ++j) {
;                 const f32x2 bu = *(const LAS f32x2*)(BU + j * 528 + lane * 8);
;                 sv = __builtin_elementwise_fma(ayn, __builtin_shufflevector(sv, sv, 1, 0), __builtin_elementwise_fma(axx, sv, bu));
;                 if (PASS == 2) *(LAS unsigned*)(SI + j * 272 + lane * 4) = cvt_pk_bf16(sv.x, sv.y);
;             }
;             if (PASS == 2) {
;                 asm volatile("s_waitcnt lgkmcnt(0)" ::: "memory");
;                 f32x4 acc = (f32x4){0.f, 0.f, 0.f, 0.f};
; #pragma unroll
;                 for (int kt = 0; kt < 4; ++kt) { const bf16x8 sv = *(const LAS bf16x8*)(SI + fr * 272 + (32 * kt + 8 * fq) * 2);
;                     acc = __builtin_amdgcn_mfma_f32_16x16x32_bf16(cf[kt], sv, acc, 0, 0, 0); }
;                 const size_t tok = tok0 + 16 * mt + fr;
;                 float o[4];
;                 const float uf[4] = {bflo(ucur.x), bfhi(ucur.x), bflo(ucur.y), bfhi(ucur.y)};
; #pragma unroll
;                 for (int j = 0; j < 4; ++j) { const float y = acc[j] + dd[j] * uf[j]; o[j] = y * fsigmoid(1.5957691216057308f * (y + 0.044715f * y * y * y)); }
;                 u32x2 w; w.x = cvt_pk_bf16(o[0], o[1]); w.y = cvt_pk_bf16(o[2], o[3]);
;                 *(u32x2*)(ypre + tok * 512 + g * 16 + 4 * fq) = w;
;             }
;             asm volatile("" ::: "memory");
;             ucur = unext;
;         }
	v_mfma_f32_32x32x16_bf16 v[88:103], v[156:159], v[38:41], 0
	v_mfma_f32_32x32x16_bf16 v[104:119], v[156:159], v[46:49], 0
	v_fma_f32 v70, v56, v54, v124
	v_fma_f32 v71, v56, v55, v230
	v_fma_f32 v80, v16, v76, v220
	v_fma_f32 v81, v17, v77, v221
	v_fma_f32 v72, v36, v55, v70
	v_fma_f32 v73, v37, v54, v71
	v_cvt_pk_bf16_f32 v74, v72, v73
	v_fma_f32 v82, v18, v78, v222
	v_fma_f32 v83, v19, v79, v223
	v_fma_f32 v70, v56, v72, v125
	v_fma_f32 v71, v56, v73, v231
	v_mul_f32_e32 v84, 0x3d372713, v80
	v_mul_f32_e32 v85, 0x3d372713, v81
	v_fma_f32 v54, v36, v73, v70
	v_fma_f32 v55, v37, v72, v71
	v_cvt_pk_bf16_f32 v75, v54, v55
	v_mul_f32_e32 v86, 0x3d372713, v82
	v_mul_f32_e32 v87, 0x3d372713, v83
	ds_write2_b32 v243, v74, v75 offset0:0 offset1:68
	v_mfma_f32_32x32x16_bf16 v[88:103], v[200:203], v[42:45], v[88:103]
	v_mfma_f32_32x32x16_bf16 v[104:119], v[200:203], v[50:53], v[104:119]
	v_fma_f32 v70, v56, v54, v126
	v_fma_f32 v71, v56, v55, v232
	v_mul_f32_e32 v84, v80, v84
	v_mul_f32_e32 v85, v81, v85
	v_fma_f32 v72, v36, v55, v70
	v_fma_f32 v73, v37, v54, v71
	v_cvt_pk_bf16_f32 v74, v72, v73
	v_mul_f32_e32 v86, v82, v86
	v_mul_f32_e32 v87, v83, v87
	v_fma_f32 v70, v56, v72, v127
	v_fma_f32 v71, v56, v73, v233
	v_fma_f32 v84, v80, v84, v80
	v_fma_f32 v85, v81, v85, v81
	v_fma_f32 v54, v36, v73, v70
	v_fma_f32 v55, v37, v72, v71
	v_cvt_pk_bf16_f32 v75, v54, v55
	v_fma_f32 v86, v82, v86, v82
	v_fma_f32 v87, v83, v87, v83
	ds_write2_b32 v243, v74, v75 offset0:136 offset1:204
	v_fma_f32 v70, v56, v54, v128
	v_fma_f32 v71, v56, v55, v234
	v_mul_f32_e32 v84, 0x3fcc422a, v84
	v_mul_f32_e32 v85, 0x3fcc422a, v85
	v_fma_f32 v72, v36, v55, v70
	v_fma_f32 v73, v37, v54, v71
	v_cvt_pk_bf16_f32 v74, v72, v73
	v_mul_f32_e32 v86, 0x3fcc422a, v86
	v_mul_f32_e32 v87, 0x3fcc422a, v87
	v_fma_f32 v70, v56, v72, v129
	v_fma_f32 v71, v56, v73, v235
	v_mul_f32_e32 v84, 0xbfb8aa3b, v84
	v_mul_f32_e32 v85, 0xbfb8aa3b, v85
	v_fma_f32 v54, v36, v73, v70
	v_fma_f32 v55, v37, v72, v71
	v_cvt_pk_bf16_f32 v75, v54, v55
	v_mul_f32_e32 v86, 0xbfb8aa3b, v86
	ds_write2_b32 v244, v74, v75 offset0:0 offset1:68
	v_fma_f32 v70, v56, v54, v130
	v_fma_f32 v71, v56, v55, v236
	v_mul_f32_e32 v87, 0xbfb8aa3b, v87
	v_exp_f32_e32 v84, v84
	v_fma_f32 v72, v36, v55, v70
	v_fma_f32 v73, v37, v54, v71
	v_cvt_pk_bf16_f32 v74, v72, v73
	v_exp_f32_e32 v85, v85
	v_exp_f32_e32 v86, v86
	v_fma_f32 v70, v56, v72, v131
	v_fma_f32 v71, v56, v73, v237
	v_exp_f32_e32 v87, v87
	v_add_f32_e32 v84, 1.0, v84
	v_fma_f32 v54, v36, v73, v70
	v_fma_f32 v55, v37, v72, v71
	v_cvt_pk_bf16_f32 v75, v54, v55
	v_add_f32_e32 v85, 1.0, v85
	ds_write2_b32 v244, v74, v75 offset0:136 offset1:204
	v_fma_f32 v70, v56, v54, v132
	v_fma_f32 v71, v56, v55, v238
	v_add_f32_e32 v86, 1.0, v86
	v_add_f32_e32 v87, 1.0, v87
	v_fma_f32 v72, v36, v55, v70
	v_fma_f32 v73, v37, v54, v71
	v_cvt_pk_bf16_f32 v74, v72, v73
	v_rcp_f32_e32 v84, v84
	v_rcp_f32_e32 v85, v85
	v_fma_f32 v70, v56, v72, v133
	v_fma_f32 v71, v56, v73, v239
	v_rcp_f32_e32 v86, v86
	v_rcp_f32_e32 v87, v87
	v_fma_f32 v54, v36, v73, v70
	v_fma_f32 v55, v37, v72, v71
	v_cvt_pk_bf16_f32 v75, v54, v55
	s_nop 0
	ds_write2_b32 v245, v74, v75 offset0:0 offset1:68
	v_fma_f32 v70, v56, v54, v134
	v_fma_f32 v71, v56, v55, v240
	v_mul_f32_e32 v84, v80, v84
	v_mul_f32_e32 v85, v81, v85
	v_fma_f32 v72, v36, v55, v70
	v_fma_f32 v73, v37, v54, v71
	v_cvt_pk_bf16_f32 v74, v72, v73
	v_mul_f32_e32 v86, v82, v86
	v_mul_f32_e32 v87, v83, v87
	v_fma_f32 v70, v56, v72, v135
	v_fma_f32 v71, v56, v73, v241
	v_cvt_pk_bf16_f32 v84, v84, v85
	v_fma_f32 v54, v36, v73, v70
	v_fma_f32 v55, v37, v72, v71
	v_cvt_pk_bf16_f32 v75, v54, v55
	v_cvt_pk_bf16_f32 v85, v86, v87
	ds_write2_b32 v245, v74, v75 offset0:136 offset1:204
	global_store_dwordx2 v[246:247], v[84:85], off
	s_mov_b64 s[18:19], 0x4000
	v_lshl_add_u64 v[246:247], v[246:247], 0, s[18:19]
	s_mov_b64 s[18:19], 0x8000
	s_addk_i32 s12, 0x80
	s_cmpk_eq_i32 s12, 0x400
	s_cbranch_scc0 .Lp2_loop
	ds_read_b128 v[192:195], v69 offset:8448
	ds_read_b128 v[204:207], v69 offset:8512
	ds_read_b128 v[212:215], v69 offset:8576
	ds_read_b128 v[216:219], v69 offset:8640
	s_waitcnt lgkmcnt(0)
	v_mfma_f32_16x16x32_bf16 v[220:223], v[0:3], v[192:195], 0
	v_mfma_f32_16x16x32_bf16 v[220:223], v[4:7], v[204:207], v[220:223]
	v_mfma_f32_16x16x32_bf16 v[220:223], v[8:11], v[212:215], v[220:223]
	v_mfma_f32_16x16x32_bf16 v[220:223], v[12:15], v[216:219], v[220:223]
	s_nop 7
	s_nop 1
	v_lshlrev_b32_e32 v76, 16, v148
	v_and_b32_e32 v77, 0xffff0000, v148
	v_lshlrev_b32_e32 v78, 16, v149
	v_and_b32_e32 v79, 0xffff0000, v149
	v_fma_f32 v80, v16, v76, v220
	v_fma_f32 v81, v17, v77, v221
	v_fma_f32 v82, v18, v78, v222
	v_fma_f32 v83, v19, v79, v223
	v_mul_f32_e32 v84, 0x3d372713, v80
	v_mul_f32_e32 v85, 0x3d372713, v81
	v_mul_f32_e32 v86, 0x3d372713, v82
	v_mul_f32_e32 v87, 0x3d372713, v83
	v_mul_f32_e32 v84, v80, v84
	v_mul_f32_e32 v85, v81, v85
	v_mul_f32_e32 v86, v82, v86
	v_mul_f32_e32 v87, v83, v87
	v_fma_f32 v84, v80, v84, v80
	v_fma_f32 v85, v81, v85, v81
	v_fma_f32 v86, v82, v86, v82
	v_fma_f32 v87, v83, v87, v83
	v_mul_f32_e32 v84, 0x3fcc422a, v84
	v_mul_f32_e32 v85, 0x3fcc422a, v85
	v_mul_f32_e32 v86, 0x3fcc422a, v86
	v_mul_f32_e32 v87, 0x3fcc422a, v87
	v_mul_f32_e32 v84, 0xbfb8aa3b, v84
	v_mul_f32_e32 v85, 0xbfb8aa3b, v85
	v_mul_f32_e32 v86, 0xbfb8aa3b, v86
	v_mul_f32_e32 v87, 0xbfb8aa3b, v87
	v_exp_f32_e32 v84, v84
	v_exp_f32_e32 v85, v85
	v_exp_f32_e32 v86, v86
	v_exp_f32_e32 v87, v87
	v_add_f32_e32 v84, 1.0, v84
	v_add_f32_e32 v85, 1.0, v85
	v_add_f32_e32 v86, 1.0, v86
	v_add_f32_e32 v87, 1.0, v87
	v_rcp_f32_e32 v84, v84
	v_rcp_f32_e32 v85, v85
	v_rcp_f32_e32 v86, v86
	v_rcp_f32_e32 v87, v87
	s_nop 0
	v_mul_f32_e32 v84, v80, v84
	v_mul_f32_e32 v85, v81, v85
	v_mul_f32_e32 v86, v82, v86
	v_mul_f32_e32 v87, v83, v87
	v_cvt_pk_bf16_f32 v84, v84, v85
	v_cvt_pk_bf16_f32 v85, v86, v87
	global_store_dwordx2 v[246:247], v[84:85], off
	s_waitcnt vmcnt(0)
	s_mov_b64 s[12:13], 0x400
	s_branch .LBB0_323

; template <int PASS> __device__ void ssm_pass(const Params& P, int l, LAS unsigned char* lds) {
;     ...
;         const int b = unit >> 4, r = (unit >> 2) & 3, g = (unit & 3) * 8 + wave;
;         const size_t tok0 = (size_t)b * SEQ + r * 1024;
;         const f32x2 a = *(const f32x2*)(lamb + (g * 64 + lane) * 2);
;         bf16x4 bf[8];
; #pragma unroll
;         for (int t = 0; t < 8; ++t) bf[t] = *(const bf16x4*)(Bfrag + ((size_t)(g * 8 + t) * 64 + lane) * 4);
;         float sr = 0.f, si = 0.f;
;         bf16x8 cf[4]; f32x4 dd;
;         if (PASS == 2) {
;             const f32x2 a1k = *(const f32x2*)(lamb1k + (g * 64 + lane) * 2);
;             for (int rr = 0; rr < r; ++rr) { const f32x2 e = *(const f32x2*)(E + ((size_t)((b * 32 + g) * 4 + rr) * 64 + lane) * 2);
;                 const float nr = a1k.x * sr - a1k.y * si + e.x, ni = a1k.x * si + a1k.y * sr + e.y; sr = nr; si = ni; }
; #pragma unroll
;             for (int kt = 0; kt < 4; ++kt) cf[kt] = *(const bf16x8*)(Cfrag + ((size_t)(g * 4 + kt) * 64 + lane) * 8);
;             dd = *(const f32x4*)(dskip + g * 16 + 4 * fq);
;         }
;         f32x2 sv = {sr, si}; const f32x2 axx = {a.x, a.x}, ayn = {-a.y, a.y};
;         const bf16_t* zrow = z + (tok0 + fr) * DM + g * 16 + 4 * fq;
;         u32x2 ucur = *(const u32x2*)zrow;
; #pragma nounroll
;         for (int mt = 0; mt < 64; ++mt) {
;             u32x2 unext = ucur; if (mt < 63) unext = *(const u32x2*)(zrow + (size_t)(mt + 1) * 16 * DM);
;             const bf16x4 af = __builtin_bit_cast(bf16x4, ucur);
;             f32x4 d[8];
; #pragma unroll
;             for (int t = 0; t < 8; ++t) d[t] = __builtin_amdgcn_mfma_f32_16x16x16bf16_1k(af, bf[t], (f32x4){0.f, 0.f, 0.f, 0.f}, 0, 0, 0);
.LBB0_339:
	s_lshl_b32 s11, s17, 3
	s_and_b32 s19, s11, 24
	s_add_i32 s19, s19, s14
	s_lshl_b32 s12, s19, 3
	s_ashr_i32 s13, s12, 31
	s_lshl_b64 s[20:21], s[12:13], 9
	v_lshl_add_u64 v[12:13], v[4:5], 0, s[20:21]
	s_or_b32 s20, s12, 1
	s_ashr_i32 s21, s20, 31
	s_lshl_b64 s[20:21], s[20:21], 9
	v_lshl_add_u64 v[14:15], v[4:5], 0, s[20:21]
	s_or_b32 s20, s12, 2
	s_ashr_i32 s21, s20, 31
	s_lshl_b64 s[20:21], s[20:21], 9
	v_lshl_add_u64 v[16:17], v[4:5], 0, s[20:21]
	s_or_b32 s20, s12, 3
	s_ashr_i32 s21, s20, 31
	s_lshl_b64 s[20:21], s[20:21], 9
	v_lshl_add_u64 v[20:21], v[4:5], 0, s[20:21]
	s_or_b32 s20, s12, 4
	s_ashr_i32 s21, s20, 31
	s_lshl_b64 s[20:21], s[20:21], 9
	v_lshl_add_u64 v[22:23], v[4:5], 0, s[20:21]
	s_or_b32 s20, s12, 5
	s_ashr_i32 s21, s20, 31
	s_lshl_b64 s[20:21], s[20:21], 9
	v_lshl_add_u64 v[24:25], v[4:5], 0, s[20:21]
	s_or_b32 s20, s12, 6
	s_or_b32 s12, s12, 7
	s_ashr_i32 s10, s17, 4
	s_ashr_i32 s13, s12, 31
	s_bfe_u32 s18, s17, 0x20002
	s_ashr_i32 s11, s10, 31
	s_lshl_b64 s[12:13], s[12:13], 9
	s_lshl_b32 s22, s18, 10
	v_lshl_add_u64 v[18:19], v[4:5], 0, s[12:13]
	s_lshl_b64 s[12:13], s[10:11], 12
	s_ashr_i32 s21, s20, 31
	s_or_b32 s11, s12, s22
	v_lshl_or_b32 v10, s19, 7, v1
	s_lshl_b64 s[20:21], s[20:21], 9
	v_mov_b32_e32 v29, s13
	v_or_b32_e32 v28, s11, v0
	v_ashrrev_i32_e32 v11, 31, v10
	v_lshl_add_u64 v[26:27], v[4:5], 0, s[20:21]
	v_lshlrev_b64 v[28:29], 11, v[28:29]
	s_lshl_b32 s20, s19, 4
	v_lshl_add_u64 v[10:11], v[10:11], 2, s[0:1]
	v_lshl_add_u64 v[28:29], s[94:95], 0, v[28:29]
	s_ashr_i32 s21, s20, 31
	global_load_dwordx2 v[10:11], v[10:11], off
	s_nop 0
	s_nop 0
	s_nop 0
	v_lshl_add_u64 v[28:29], s[20:21], 1, v[28:29]
	v_lshl_add_u64 v[28:29], v[28:29], 0, v[168:169]
	s_nop 0
	global_load_dwordx2 v[36:37], v[28:29], off
	s_nop 0
	s_nop 0
	s_nop 0
	s_nop 0
	v_and_b32_e32 v72, 16, v162
	v_mul_u32_u24_e32 v72, 24, v72
	v_mov_b32_e32 v73, 0
	v_lshl_add_u64 v[70:71], v[12:13], 0, v[72:73]
	global_load_dwordx2 v[12:13], v[70:71], off
	global_load_dwordx2 v[14:15], v[70:71], off offset:128
	global_load_dwordx2 v[16:17], v[70:71], off offset:1024
	global_load_dwordx2 v[18:19], v[70:71], off offset:1152
	global_load_dwordx2 v[20:21], v[70:71], off offset:2048
	global_load_dwordx2 v[22:23], v[70:71], off offset:2176
	global_load_dwordx2 v[24:25], v[70:71], off offset:3072
	global_load_dwordx2 v[26:27], v[70:71], off offset:3200
	v_lshlrev_b32_e32 v28, 4, v3
	v_and_b32_e32 v28, 0x180, v28
	v_or_b32_e32 v30, s12, v0
	v_add_u32_e32 v28, s16, v28
	v_mov_b32_e32 v31, s13
	v_or_b32_e32 v30, s22, v30
	v_ashrrev_i32_e32 v29, 31, v28
	v_lshlrev_b64 v[30:31], 11, v[30:31]
	v_lshl_add_u64 v[28:29], v[28:29], 1, v[30:31]
	v_mov_b32_e32 v34, 0
	v_lshl_add_u64 v[28:29], v[8:9], 0, v[28:29]
	s_mov_b64 s[12:13], 0
	v_mov_b32_e32 v35, v34
	s_waitcnt vmcnt(0)
	v_mov_b32_e32 v30, v10
	v_mov_b32_e32 v31, v10
	v_xor_b32_e32 v10, 0x80000000, v11
	v_mov_b64_e32 v[32:33], v[36:37]
	v_and_b32_e32 v70, 48, v208
	v_lshrrev_b32_e32 v70, 1, v70
	v_lshl_add_u32 v71, v0, 5, s15
	v_add_u32_e32 v146, v71, v70
	v_bfe_u32 v71, v208, 2, 1
	v_xor_b32_e32 v73, 1, v71
	v_mov_b32_e32 v72, v71
	v_and_b32_e32 v70, 3, v208
	v_lshrrev_b32_e32 v74, 1, v208
	v_and_b32_e32 v74, 12, v74
	v_add_u32_e32 v70, v70, v74
	v_lshl_add_u32 v70, v70, 5, s15
	v_and_b32_e32 v71, 32, v208
	v_lshrrev_b32_e32 v71, 1, v71
	v_add_u32_e32 v70, v70, v71
	v_mov_b32_e32 v71, s15
	v_add_u32_e32 v71, 0x200, v71
	v_cmp_eq_u32_e32 vcc, 0, v72
	s_nop 1
	v_cndmask_b32_e32 v196, v71, v70, vcc
	v_cmp_eq_u32_e32 vcc, 0, v73
	s_nop 1
	v_cndmask_b32_e32 v197, v71, v70, vcc
	v_mov_b32_e32 v72, 0
	v_mov_b32_e32 v73, 0
	v_mov_b32_e32 v74, 0
	v_mov_b32_e32 v75, 0
	v_lshl_add_u32 v70, v208, 4, s15
	ds_write_b128 v70, v[72:75] offset:512
	v_mov_b64_e32 v[54:55], v[28:29]
	s_lshl_b32 s22, s2, 26
	s_mov_b32 s23, 0
	v_lshl_add_u64 v[56:57], v[172:173], 0, s[22:23]
	v_readlane_b32 s22, v253, 8
	v_readlane_b32 s23, v253, 9
	s_nop 1
	v_lshl_add_u64 v[58:59], s[22:23], 0, v[170:171]
	ds_write_b64 v146, v[36:37]
	ds_read_b128 v[156:159], v196
	ds_read_b128 v[200:203], v197
	s_mov_b64 s[20:21], 0x8000
	global_load_dwordx2 v[40:41], v[54:55], off
	global_load_dwordx2 v[144:145], v[54:55], off
	v_lshl_add_u64 v[54:55], v[54:55], 0, s[20:21]
	global_load_dwordx2 v[42:43], v[54:55], off
	global_load_dwordx2 v[144:145], v[54:55], off
	v_lshl_add_u64 v[54:55], v[54:55], 0, s[20:21]
	global_load_dwordx2 v[44:45], v[54:55], off
	global_load_dwordx2 v[144:145], v[54:55], off
	v_lshl_add_u64 v[54:55], v[54:55], 0, s[20:21]
	global_load_dwordx2 v[46:47], v[54:55], off
	global_load_dwordx2 v[144:145], v[54:55], off
	v_lshl_add_u64 v[54:55], v[54:55], 0, s[20:21]
	global_load_dwordx2 v[48:49], v[54:55], off
	global_load_dwordx2 v[144:145], v[54:55], off
	v_lshl_add_u64 v[54:55], v[54:55], 0, s[20:21]
	s_waitcnt lgkmcnt(0)
	v_mfma_f32_32x32x16_bf16 v[88:103], v[156:159], v[12:15], 0
	v_mfma_f32_32x32x16_bf16 v[104:119], v[156:159], v[20:23], 0
	v_mfma_f32_32x32x16_bf16 v[88:103], v[200:203], v[16:19], v[88:103]
	v_mfma_f32_32x32x16_bf16 v[104:119], v[200:203], v[24:27], v[104:119]
	s_nop 7
	s_mov_b32 s12, 0
; #define LAS __attribute__((address_space(3)))
; __device__ __forceinline__ unsigned cvt_pk_bf16(float lo, float hi) { const f32x2 v = {lo, hi}; return __builtin_bit_cast(unsigned, __builtin_convertvector(v, bfx2_t)); }
; __device__ __forceinline__ void conv_p(const Params& P, int l) {
;     ...
;     for (; i + 3 * stride < n8; i += 4 * stride) {
;         f32x4 a[4], b[4];
; #pragma unroll
;         for (int q = 0; q < 4; ++q) { a[q] = *(const f32x4*)(src + (i + q * stride) * 8); b[q] = *(const f32x4*)(src + (i + q * stride) * 8 + 4); }
; #pragma unroll
;         for (int q = 0; q < 4; ++q) { u32x4 w; w.x = cvt_pk_bf16(a[q][0], a[q][1]); w.y = cvt_pk_bf16(a[q][2], a[q][3]); w.z = cvt_pk_bf16(b[q][0], b[q][1]); w.w = cvt_pk_bf16(b[q][2], b[q][3]);
;             *(u32x4*)(dst + (i + q * stride) * 8) = w; }
; template <int PASS> __device__ void ssm_pass(const Params& P, int l, LAS unsigned char* lds) {
;     ...
;         for (int mt = 0; mt < 64; ++mt) {
;             u32x2 unext = ucur; if (mt < 63) unext = *(const u32x2*)(zrow + (size_t)(mt + 1) * 16 * DM);
;             const bf16x4 af = __builtin_bit_cast(bf16x4, ucur);
;             f32x4 d[8];
; #pragma unroll
;             for (int t = 0; t < 8; ++t) d[t] = __builtin_amdgcn_mfma_f32_16x16x16bf16_1k(af, bf[t], (f32x4){0.f, 0.f, 0.f, 0.f}, 0, 0, 0);
; #pragma unroll
;             for (int tq = 0; tq < 4; ++tq)
; #pragma unroll
;                 for (int j = 0; j < 4; ++j) *(LAS f32x2*)(BU + (4 * fq + j) * 528 + (16 * tq + fr) * 8) = (f32x2){d[tq][j], d[tq + 4][j]};
;             asm volatile("s_waitcnt lgkmcnt(0)" ::: "memory");
; #pragma unroll
;             for (int j = 0; j < 16; ++j) {
;                 const f32x2 bu = *(const LAS f32x2*)(BU + j * 528 + lane * 8);
;                 sv = __builtin_elementwise_fma(ayn, __builtin_shufflevector(sv, sv, 1, 0), __builtin_elementwise_fma(axx, sv, bu));
;                 if (PASS == 2) *(LAS unsigned*)(SI + j * 272 + lane * 4) = cvt_pk_bf16(sv.x, sv.y);
;             }
.Lp1_loop:
	s_waitcnt vmcnt(9)
	ds_write_b64 v146, v[40:41]
	ds_read_b128 v[156:159], v196
	ds_read_b128 v[200:203], v197
	global_load_dwordx2 v[50:51], v[54:55], off
	v_lshl_add_u64 v[54:55], v[54:55], 0, s[20:21]
	global_load_dwordx4 v[60:63], v[56:57], off
	v_fma_f32 v70, v30, v34, v88
	v_fma_f32 v71, v30, v35, v104
	v_fma_f32 v72, v10, v35, v70
	v_fma_f32 v73, v11, v34, v71
	v_fma_f32 v70, v30, v72, v89
	v_fma_f32 v71, v30, v73, v105
	v_fma_f32 v34, v10, v73, v70
	v_fma_f32 v35, v11, v72, v71
	v_fma_f32 v70, v30, v34, v90
	v_fma_f32 v71, v30, v35, v106
	v_fma_f32 v72, v10, v35, v70
	v_fma_f32 v73, v11, v34, v71
	v_fma_f32 v70, v30, v72, v91
	v_fma_f32 v71, v30, v73, v107
	v_fma_f32 v34, v10, v73, v70
	v_fma_f32 v35, v11, v72, v71
	s_waitcnt lgkmcnt(0)
	v_mfma_f32_32x32x16_bf16 v[120:135], v[156:159], v[12:15], 0
	v_mfma_f32_32x32x16_bf16 v[226:241], v[156:159], v[20:23], 0
	v_fma_f32 v70, v30, v34, v92
	v_fma_f32 v71, v30, v35, v108
	v_fma_f32 v72, v10, v35, v70
	v_fma_f32 v73, v11, v34, v71
	v_fma_f32 v70, v30, v72, v93
	v_fma_f32 v71, v30, v73, v109
	v_fma_f32 v34, v10, v73, v70
	v_fma_f32 v35, v11, v72, v71
	v_fma_f32 v70, v30, v34, v94
	v_fma_f32 v71, v30, v35, v110
	v_fma_f32 v72, v10, v35, v70
	v_fma_f32 v73, v11, v34, v71
	v_fma_f32 v70, v30, v72, v95
	v_fma_f32 v71, v30, v73, v111
	v_fma_f32 v34, v10, v73, v70
	v_fma_f32 v35, v11, v72, v71
	v_mfma_f32_32x32x16_bf16 v[120:135], v[200:203], v[16:19], v[120:135]
	v_mfma_f32_32x32x16_bf16 v[226:241], v[200:203], v[24:27], v[226:241]
	v_fma_f32 v70, v30, v34, v96
	v_fma_f32 v71, v30, v35, v112
	v_fma_f32 v72, v10, v35, v70
	v_fma_f32 v73, v11, v34, v71
	v_fma_f32 v70, v30, v72, v97
	v_fma_f32 v71, v30, v73, v113
	v_fma_f32 v34, v10, v73, v70
	v_fma_f32 v35, v11, v72, v71
	v_fma_f32 v70, v30, v34, v98
	v_fma_f32 v71, v30, v35, v114
	v_fma_f32 v72, v10, v35, v70
	v_fma_f32 v73, v11, v34, v71
	v_fma_f32 v70, v30, v72, v99
	v_fma_f32 v71, v30, v73, v115
	v_fma_f32 v34, v10, v73, v70
	v_fma_f32 v35, v11, v72, v71
	v_fma_f32 v70, v30, v34, v100
	v_fma_f32 v71, v30, v35, v116
	v_fma_f32 v72, v10, v35, v70
	v_fma_f32 v73, v11, v34, v71
	v_fma_f32 v70, v30, v72, v101
	v_fma_f32 v71, v30, v73, v117
	v_fma_f32 v34, v10, v73, v70
	v_fma_f32 v35, v11, v72, v71
	v_fma_f32 v70, v30, v34, v102
	v_fma_f32 v71, v30, v35, v118
	v_fma_f32 v72, v10, v35, v70
	v_fma_f32 v73, v11, v34, v71
	v_fma_f32 v70, v30, v72, v103
	v_fma_f32 v71, v30, v73, v119
	v_fma_f32 v34, v10, v73, v70
	v_fma_f32 v35, v11, v72, v71
	s_waitcnt vmcnt(9)
	ds_write_b64 v146, v[42:43]
	ds_read_b128 v[156:159], v196
	ds_read_b128 v[200:203], v197
	global_load_dwordx2 v[52:53], v[54:55], off
	v_lshl_add_u64 v[54:55], v[54:55], 0, s[20:21]
	global_load_dwordx4 v[64:67], v[56:57], off offset:16
	s_mov_b64 s[22:23], 0x400000
	v_lshl_add_u64 v[56:57], v[56:57], 0, s[22:23]
	v_fma_f32 v70, v30, v34, v120
	v_fma_f32 v71, v30, v35, v226
	v_fma_f32 v72, v10, v35, v70
	v_fma_f32 v73, v11, v34, v71
	v_fma_f32 v70, v30, v72, v121
	v_fma_f32 v71, v30, v73, v227
	v_fma_f32 v34, v10, v73, v70
	v_fma_f32 v35, v11, v72, v71
	v_fma_f32 v70, v30, v34, v122
	v_fma_f32 v71, v30, v35, v228
	v_fma_f32 v72, v10, v35, v70
	v_fma_f32 v73, v11, v34, v71
	v_fma_f32 v70, v30, v72, v123
	v_fma_f32 v71, v30, v73, v229
	v_fma_f32 v34, v10, v73, v70
	v_fma_f32 v35, v11, v72, v71
	s_waitcnt lgkmcnt(0)
; #define LAS __attribute__((address_space(3)))
; __device__ __forceinline__ unsigned cvt_pk_bf16(float lo, float hi) { const f32x2 v = {lo, hi}; return __builtin_bit_cast(unsigned, __builtin_convertvector(v, bfx2_t)); }
; __device__ __forceinline__ void conv_p(const Params& P, int l) {
;     ...
;     for (; i + 3 * stride < n8; i += 4 * stride) {
;         f32x4 a[4], b[4];
; #pragma unroll
;         for (int q = 0; q < 4; ++q) { a[q] = *(const f32x4*)(src + (i + q * stride) * 8); b[q] = *(const f32x4*)(src + (i + q * stride) * 8 + 4); }
; #pragma unroll
;         for (int q = 0; q < 4; ++q) { u32x4 w; w.x = cvt_pk_bf16(a[q][0], a[q][1]); w.y = cvt_pk_bf16(a[q][2], a[q][3]); w.z = cvt_pk_bf16(b[q][0], b[q][1]); w.w = cvt_pk_bf16(b[q][2], b[q][3]);
;             *(u32x4*)(dst + (i + q * stride) * 8) = w; }
; template <int PASS> __device__ void ssm_pass(const Params& P, int l, LAS unsigned char* lds) {
;     ...
;         for (int mt = 0; mt < 64; ++mt) {
;             u32x2 unext = ucur; if (mt < 63) unext = *(const u32x2*)(zrow + (size_t)(mt + 1) * 16 * DM);
;             const bf16x4 af = __builtin_bit_cast(bf16x4, ucur);
;             f32x4 d[8];
; #pragma unroll
;             for (int t = 0; t < 8; ++t) d[t] = __builtin_amdgcn_mfma_f32_16x16x16bf16_1k(af, bf[t], (f32x4){0.f, 0.f, 0.f, 0.f}, 0, 0, 0);
; #pragma unroll
;             for (int tq = 0; tq < 4; ++tq)
; #pragma unroll
;                 for (int j = 0; j < 4; ++j) *(LAS f32x2*)(BU + (4 * fq + j) * 528 + (16 * tq + fr) * 8) = (f32x2){d[tq][j], d[tq + 4][j]};
;             asm volatile("s_waitcnt lgkmcnt(0)" ::: "memory");
; #pragma unroll
;             for (int j = 0; j < 16; ++j) {
;                 const f32x2 bu = *(const LAS f32x2*)(BU + j * 528 + lane * 8);
;                 sv = __builtin_elementwise_fma(ayn, __builtin_shufflevector(sv, sv, 1, 0), __builtin_elementwise_fma(axx, sv, bu));
;                 if (PASS == 2) *(LAS unsigned*)(SI + j * 272 + lane * 4) = cvt_pk_bf16(sv.x, sv.y);
;             }
	v_mfma_f32_32x32x16_bf16 v[88:103], v[156:159], v[12:15], 0
	v_mfma_f32_32x32x16_bf16 v[104:119], v[156:159], v[20:23], 0
	v_fma_f32 v70, v30, v34, v124
	v_fma_f32 v71, v30, v35, v230
	v_fma_f32 v72, v10, v35, v70
	v_fma_f32 v73, v11, v34, v71
	v_fma_f32 v70, v30, v72, v125
	v_fma_f32 v71, v30, v73, v231
	v_fma_f32 v34, v10, v73, v70
	v_fma_f32 v35, v11, v72, v71
	v_fma_f32 v70, v30, v34, v126
	v_fma_f32 v71, v30, v35, v232
	v_fma_f32 v72, v10, v35, v70
	v_fma_f32 v73, v11, v34, v71
	v_fma_f32 v70, v30, v72, v127
	v_fma_f32 v71, v30, v73, v233
	v_fma_f32 v34, v10, v73, v70
	v_fma_f32 v35, v11, v72, v71
	v_mfma_f32_32x32x16_bf16 v[88:103], v[200:203], v[16:19], v[88:103]
	v_mfma_f32_32x32x16_bf16 v[104:119], v[200:203], v[24:27], v[104:119]
	v_fma_f32 v70, v30, v34, v128
	v_fma_f32 v71, v30, v35, v234
	v_fma_f32 v72, v10, v35, v70
	v_fma_f32 v73, v11, v34, v71
	v_fma_f32 v70, v30, v72, v129
	v_fma_f32 v71, v30, v73, v235
	v_fma_f32 v34, v10, v73, v70
	v_fma_f32 v35, v11, v72, v71
	v_fma_f32 v70, v30, v34, v130
	v_fma_f32 v71, v30, v35, v236
	v_fma_f32 v72, v10, v35, v70
	v_fma_f32 v73, v11, v34, v71
	v_fma_f32 v70, v30, v72, v131
	v_fma_f32 v71, v30, v73, v237
	v_fma_f32 v34, v10, v73, v70
	v_fma_f32 v35, v11, v72, v71
	v_fma_f32 v70, v30, v34, v132
	v_fma_f32 v71, v30, v35, v238
	v_fma_f32 v72, v10, v35, v70
	v_fma_f32 v73, v11, v34, v71
	v_fma_f32 v70, v30, v72, v133
	v_fma_f32 v71, v30, v73, v239
	v_fma_f32 v34, v10, v73, v70
	v_fma_f32 v35, v11, v72, v71
	v_fma_f32 v70, v30, v34, v134
	v_fma_f32 v71, v30, v35, v240
	v_fma_f32 v72, v10, v35, v70
	v_fma_f32 v73, v11, v34, v71
	v_fma_f32 v70, v30, v72, v135
	v_fma_f32 v71, v30, v73, v241
	v_fma_f32 v34, v10, v73, v70
	v_fma_f32 v35, v11, v72, v71
	s_waitcnt vmcnt(9)
	ds_write_b64 v146, v[44:45]
	ds_read_b128 v[156:159], v196
	ds_read_b128 v[200:203], v197
	global_load_dwordx2 v[36:37], v[54:55], off
	v_lshl_add_u64 v[54:55], v[54:55], 0, s[20:21]
	global_load_dwordx2 v[144:145], v[54:55], off
	v_fma_f32 v70, v30, v34, v88
	v_fma_f32 v71, v30, v35, v104
	v_fma_f32 v72, v10, v35, v70
	v_fma_f32 v73, v11, v34, v71
	v_fma_f32 v70, v30, v72, v89
	v_fma_f32 v71, v30, v73, v105
	v_fma_f32 v34, v10, v73, v70
	v_fma_f32 v35, v11, v72, v71
	v_fma_f32 v70, v30, v34, v90
	v_fma_f32 v71, v30, v35, v106
	v_fma_f32 v72, v10, v35, v70
	v_fma_f32 v73, v11, v34, v71
	v_fma_f32 v70, v30, v72, v91
	v_fma_f32 v71, v30, v73, v107
	v_fma_f32 v34, v10, v73, v70
	v_fma_f32 v35, v11, v72, v71
	s_waitcnt lgkmcnt(0)
	v_mfma_f32_32x32x16_bf16 v[120:135], v[156:159], v[12:15], 0
	v_mfma_f32_32x32x16_bf16 v[226:241], v[156:159], v[20:23], 0
	v_fma_f32 v70, v30, v34, v92
	v_fma_f32 v71, v30, v35, v108
	v_fma_f32 v72, v10, v35, v70
	v_fma_f32 v73, v11, v34, v71
	v_fma_f32 v70, v30, v72, v93
	v_fma_f32 v71, v30, v73, v109
	v_fma_f32 v34, v10, v73, v70
	v_fma_f32 v35, v11, v72, v71
	v_fma_f32 v70, v30, v34, v94
	v_fma_f32 v71, v30, v35, v110
	v_fma_f32 v72, v10, v35, v70
	v_fma_f32 v73, v11, v34, v71
	v_fma_f32 v70, v30, v72, v95
	v_fma_f32 v71, v30, v73, v111
	v_fma_f32 v34, v10, v73, v70
	v_fma_f32 v35, v11, v72, v71
	v_mfma_f32_32x32x16_bf16 v[120:135], v[200:203], v[16:19], v[120:135]
	v_mfma_f32_32x32x16_bf16 v[226:241], v[200:203], v[24:27], v[226:241]
	v_fma_f32 v70, v30, v34, v96
	v_fma_f32 v71, v30, v35, v112
	v_fma_f32 v72, v10, v35, v70
	v_fma_f32 v73, v11, v34, v71
	v_fma_f32 v70, v30, v72, v97
	v_fma_f32 v71, v30, v73, v113
	v_fma_f32 v34, v10, v73, v70
	v_fma_f32 v35, v11, v72, v71
	v_fma_f32 v70, v30, v34, v98
	v_fma_f32 v71, v30, v35, v114
	v_fma_f32 v72, v10, v35, v70
	v_fma_f32 v73, v11, v34, v71
	v_fma_f32 v70, v30, v72, v99
	v_fma_f32 v71, v30, v73, v115
	v_fma_f32 v34, v10, v73, v70
	v_fma_f32 v35, v11, v72, v71
	v_fma_f32 v70, v30, v34, v100
	v_fma_f32 v71, v30, v35, v116
	v_fma_f32 v72, v10, v35, v70
	v_fma_f32 v73, v11, v34, v71
	v_fma_f32 v70, v30, v72, v101
	v_fma_f32 v71, v30, v73, v117
	v_fma_f32 v34, v10, v73, v70
	v_fma_f32 v35, v11, v72, v71
	v_fma_f32 v70, v30, v34, v102
	v_fma_f32 v71, v30, v35, v118
	v_fma_f32 v72, v10, v35, v70
	v_fma_f32 v73, v11, v34, v71
	v_fma_f32 v70, v30, v72, v103
	v_fma_f32 v71, v30, v73, v119
	v_fma_f32 v34, v10, v73, v70
	v_fma_f32 v35, v11, v72, v71
	s_waitcnt vmcnt(9)
	ds_write_b64 v146, v[46:47]
	ds_read_b128 v[156:159], v196
	ds_read_b128 v[200:203], v197
	global_load_dwordx2 v[40:41], v[54:55], off
	v_lshl_add_u64 v[54:55], v[54:55], 0, s[20:21]
	s_cmp_eq_u32 s12, 0
	s_cbranch_scc1 .Lp1_skip
	v_cvt_pk_bf16_f32 v82, v74, v75
	v_cvt_pk_bf16_f32 v83, v76, v77
	v_cvt_pk_bf16_f32 v84, v78, v79
	v_cvt_pk_bf16_f32 v85, v80, v81
	global_store_dwordx4 v[58:59], v[82:85], off
	s_mov_b64 s[22:23], 0x200000
	v_lshl_add_u64 v[58:59], v[58:59], 0, s[22:23]
	s_branch .Lp1_join

; #define LAS __attribute__((address_space(3)))
; __device__ __forceinline__ unsigned cvt_pk_bf16(float lo, float hi) { const f32x2 v = {lo, hi}; return __builtin_bit_cast(unsigned, __builtin_convertvector(v, bfx2_t)); }
; __device__ __forceinline__ void conv_p(const Params& P, int l) {
;     ...
;     for (; i + 3 * stride < n8; i += 4 * stride) {
;         f32x4 a[4], b[4];
; #pragma unroll
;         for (int q = 0; q < 4; ++q) { a[q] = *(const f32x4*)(src + (i + q * stride) * 8); b[q] = *(const f32x4*)(src + (i + q * stride) * 8 + 4); }
; #pragma unroll
;         for (int q = 0; q < 4; ++q) { u32x4 w; w.x = cvt_pk_bf16(a[q][0], a[q][1]); w.y = cvt_pk_bf16(a[q][2], a[q][3]); w.z = cvt_pk_bf16(b[q][0], b[q][1]); w.w = cvt_pk_bf16(b[q][2], b[q][3]);
;             *(u32x4*)(dst + (i + q * stride) * 8) = w; }
; template <int PASS> __device__ void ssm_pass(const Params& P, int l, LAS unsigned char* lds) {
;     ...
;         for (int mt = 0; mt < 64; ++mt) {
;             u32x2 unext = ucur; if (mt < 63) unext = *(const u32x2*)(zrow + (size_t)(mt + 1) * 16 * DM);
;             const bf16x4 af = __builtin_bit_cast(bf16x4, ucur);
;             f32x4 d[8];
; #pragma unroll
;             for (int t = 0; t < 8; ++t) d[t] = __builtin_amdgcn_mfma_f32_16x16x16bf16_1k(af, bf[t], (f32x4){0.f, 0.f, 0.f, 0.f}, 0, 0, 0);
; #pragma unroll
;             for (int tq = 0; tq < 4; ++tq)
; #pragma unroll
;                 for (int j = 0; j < 4; ++j) *(LAS f32x2*)(BU + (4 * fq + j) * 528 + (16 * tq + fr) * 8) = (f32x2){d[tq][j], d[tq + 4][j]};
;             asm volatile("s_waitcnt lgkmcnt(0)" ::: "memory");
; #pragma unroll
;             for (int j = 0; j < 16; ++j) {
;                 const f32x2 bu = *(const LAS f32x2*)(BU + j * 528 + lane * 8);
;                 sv = __builtin_elementwise_fma(ayn, __builtin_shufflevector(sv, sv, 1, 0), __builtin_elementwise_fma(axx, sv, bu));
;                 if (PASS == 2) *(LAS unsigned*)(SI + j * 272 + lane * 4) = cvt_pk_bf16(sv.x, sv.y);
;             }
.Lp1_join:
	v_fma_f32 v70, v30, v34, v120
	v_fma_f32 v71, v30, v35, v226
	v_fma_f32 v72, v10, v35, v70
	v_fma_f32 v73, v11, v34, v71
	v_fma_f32 v70, v30, v72, v121
	v_fma_f32 v71, v30, v73, v227
	v_fma_f32 v34, v10, v73, v70
	v_fma_f32 v35, v11, v72, v71
	v_fma_f32 v70, v30, v34, v122
	v_fma_f32 v71, v30, v35, v228
	v_fma_f32 v72, v10, v35, v70
	v_fma_f32 v73, v11, v34, v71
	v_fma_f32 v70, v30, v72, v123
	v_fma_f32 v71, v30, v73, v229
	v_fma_f32 v34, v10, v73, v70
	v_fma_f32 v35, v11, v72, v71
	s_waitcnt lgkmcnt(0)
	v_mfma_f32_32x32x16_bf16 v[88:103], v[156:159], v[12:15], 0
	v_mfma_f32_32x32x16_bf16 v[104:119], v[156:159], v[20:23], 0
	v_fma_f32 v70, v30, v34, v124
	v_fma_f32 v71, v30, v35, v230
	v_fma_f32 v72, v10, v35, v70
	v_fma_f32 v73, v11, v34, v71
	v_fma_f32 v70, v30, v72, v125
	v_fma_f32 v71, v30, v73, v231
	v_fma_f32 v34, v10, v73, v70
	v_fma_f32 v35, v11, v72, v71
	v_fma_f32 v70, v30, v34, v126
	v_fma_f32 v71, v30, v35, v232
	v_fma_f32 v72, v10, v35, v70
	v_fma_f32 v73, v11, v34, v71
	v_fma_f32 v70, v30, v72, v127
	v_fma_f32 v71, v30, v73, v233
	v_fma_f32 v34, v10, v73, v70
	v_fma_f32 v35, v11, v72, v71
	v_mfma_f32_32x32x16_bf16 v[88:103], v[200:203], v[16:19], v[88:103]
	v_mfma_f32_32x32x16_bf16 v[104:119], v[200:203], v[24:27], v[104:119]
	v_fma_f32 v70, v30, v34, v128
	v_fma_f32 v71, v30, v35, v234
	v_fma_f32 v72, v10, v35, v70
	v_fma_f32 v73, v11, v34, v71
	v_fma_f32 v70, v30, v72, v129
	v_fma_f32 v71, v30, v73, v235
	v_fma_f32 v34, v10, v73, v70
	v_fma_f32 v35, v11, v72, v71
	v_fma_f32 v70, v30, v34, v130
	v_fma_f32 v71, v30, v35, v236
	v_fma_f32 v72, v10, v35, v70
	v_fma_f32 v73, v11, v34, v71
	v_fma_f32 v70, v30, v72, v131
	v_fma_f32 v71, v30, v73, v237
	v_fma_f32 v34, v10, v73, v70
	v_fma_f32 v35, v11, v72, v71
	v_fma_f32 v70, v30, v34, v132
	v_fma_f32 v71, v30, v35, v238
	v_fma_f32 v72, v10, v35, v70
	v_fma_f32 v73, v11, v34, v71
	v_fma_f32 v70, v30, v72, v133
	v_fma_f32 v71, v30, v73, v239
	v_fma_f32 v34, v10, v73, v70
	v_fma_f32 v35, v11, v72, v71
	v_fma_f32 v70, v30, v34, v134
	v_fma_f32 v71, v30, v35, v240
	v_fma_f32 v72, v10, v35, v70
	v_fma_f32 v73, v11, v34, v71
	v_fma_f32 v70, v30, v72, v135
	v_fma_f32 v71, v30, v73, v241
	v_fma_f32 v34, v10, v73, v70
	v_fma_f32 v35, v11, v72, v71
	s_waitcnt vmcnt(9)
	ds_write_b64 v146, v[48:49]
	ds_read_b128 v[156:159], v196
	ds_read_b128 v[200:203], v197
	global_load_dwordx2 v[42:43], v[54:55], off
	v_lshl_add_u64 v[54:55], v[54:55], 0, s[20:21]
	global_load_dwordx4 v[74:77], v[56:57], off
	v_fma_f32 v70, v30, v34, v88
	v_fma_f32 v71, v30, v35, v104
	v_fma_f32 v72, v10, v35, v70
	v_fma_f32 v73, v11, v34, v71
	v_fma_f32 v70, v30, v72, v89
	v_fma_f32 v71, v30, v73, v105
	v_fma_f32 v34, v10, v73, v70
	v_fma_f32 v35, v11, v72, v71
	v_fma_f32 v70, v30, v34, v90
	v_fma_f32 v71, v30, v35, v106
	v_fma_f32 v72, v10, v35, v70
	v_fma_f32 v73, v11, v34, v71
	v_fma_f32 v70, v30, v72, v91
	v_fma_f32 v71, v30, v73, v107
	v_fma_f32 v34, v10, v73, v70
	v_fma_f32 v35, v11, v72, v71
	s_waitcnt lgkmcnt(0)
	v_mfma_f32_32x32x16_bf16 v[120:135], v[156:159], v[12:15], 0
	v_mfma_f32_32x32x16_bf16 v[226:241], v[156:159], v[20:23], 0
	v_fma_f32 v70, v30, v34, v92
	v_fma_f32 v71, v30, v35, v108
	v_fma_f32 v72, v10, v35, v70
	v_fma_f32 v73, v11, v34, v71
	v_fma_f32 v70, v30, v72, v93
	v_fma_f32 v71, v30, v73, v109
	v_fma_f32 v34, v10, v73, v70
	v_fma_f32 v35, v11, v72, v71
	v_fma_f32 v70, v30, v34, v94
	v_fma_f32 v71, v30, v35, v110
	v_fma_f32 v72, v10, v35, v70
	v_fma_f32 v73, v11, v34, v71
	v_fma_f32 v70, v30, v72, v95
	v_fma_f32 v71, v30, v73, v111
	v_fma_f32 v34, v10, v73, v70
	v_fma_f32 v35, v11, v72, v71
	v_mfma_f32_32x32x16_bf16 v[120:135], v[200:203], v[16:19], v[120:135]
	v_mfma_f32_32x32x16_bf16 v[226:241], v[200:203], v[24:27], v[226:241]
	v_fma_f32 v70, v30, v34, v96
	v_fma_f32 v71, v30, v35, v112
	v_fma_f32 v72, v10, v35, v70
	v_fma_f32 v73, v11, v34, v71
	v_fma_f32 v70, v30, v72, v97
	v_fma_f32 v71, v30, v73, v113
	v_fma_f32 v34, v10, v73, v70
	v_fma_f32 v35, v11, v72, v71
	v_fma_f32 v70, v30, v34, v98
	v_fma_f32 v71, v30, v35, v114
	v_fma_f32 v72, v10, v35, v70
	v_fma_f32 v73, v11, v34, v71
	v_fma_f32 v70, v30, v72, v99
	v_fma_f32 v71, v30, v73, v115
	v_fma_f32 v34, v10, v73, v70
	v_fma_f32 v35, v11, v72, v71
	v_fma_f32 v70, v30, v34, v100
	v_fma_f32 v71, v30, v35, v116
	v_fma_f32 v72, v10, v35, v70
	v_fma_f32 v73, v11, v34, v71
	v_fma_f32 v70, v30, v72, v101
	v_fma_f32 v71, v30, v73, v117
	v_fma_f32 v34, v10, v73, v70
	v_fma_f32 v35, v11, v72, v71
	v_fma_f32 v70, v30, v34, v102
	v_fma_f32 v71, v30, v35, v118
	v_fma_f32 v72, v10, v35, v70
	v_fma_f32 v73, v11, v34, v71
	v_fma_f32 v70, v30, v72, v103
	v_fma_f32 v71, v30, v73, v119
	v_fma_f32 v34, v10, v73, v70
	v_fma_f32 v35, v11, v72, v71
	s_waitcnt vmcnt(9)
	ds_write_b64 v146, v[50:51]
	ds_read_b128 v[156:159], v196
	ds_read_b128 v[200:203], v197
	global_load_dwordx2 v[44:45], v[54:55], off
	v_lshl_add_u64 v[54:55], v[54:55], 0, s[20:21]
	global_load_dwordx4 v[78:81], v[56:57], off offset:16
	s_mov_b64 s[22:23], 0x400000
	v_lshl_add_u64 v[56:57], v[56:57], 0, s[22:23]
	v_fma_f32 v70, v30, v34, v120
	v_fma_f32 v71, v30, v35, v226
	v_fma_f32 v72, v10, v35, v70
	v_fma_f32 v73, v11, v34, v71
	v_fma_f32 v70, v30, v72, v121
	v_fma_f32 v71, v30, v73, v227
	v_fma_f32 v34, v10, v73, v70
	v_fma_f32 v35, v11, v72, v71
	v_fma_f32 v70, v30, v34, v122
	v_fma_f32 v71, v30, v35, v228
	v_fma_f32 v72, v10, v35, v70
	v_fma_f32 v73, v11, v34, v71
	v_fma_f32 v70, v30, v72, v123
	v_fma_f32 v71, v30, v73, v229
	v_fma_f32 v34, v10, v73, v70
	v_fma_f32 v35, v11, v72, v71
	s_waitcnt lgkmcnt(0)
; #define LAS __attribute__((address_space(3)))
; __device__ __forceinline__ unsigned cvt_pk_bf16(float lo, float hi) { const f32x2 v = {lo, hi}; return __builtin_bit_cast(unsigned, __builtin_convertvector(v, bfx2_t)); }
; __device__ __forceinline__ void conv_p(const Params& P, int l) {
;     ...
;     for (; i + 3 * stride < n8; i += 4 * stride) {
;         f32x4 a[4], b[4];
; #pragma unroll
;         for (int q = 0; q < 4; ++q) { a[q] = *(const f32x4*)(src + (i + q * stride) * 8); b[q] = *(const f32x4*)(src + (i + q * stride) * 8 + 4); }
; #pragma unroll
;         for (int q = 0; q < 4; ++q) { u32x4 w; w.x = cvt_pk_bf16(a[q][0], a[q][1]); w.y = cvt_pk_bf16(a[q][2], a[q][3]); w.z = cvt_pk_bf16(b[q][0], b[q][1]); w.w = cvt_pk_bf16(b[q][2], b[q][3]);
;             *(u32x4*)(dst + (i + q * stride) * 8) = w; }
; template <int PASS> __device__ void ssm_pass(const Params& P, int l, LAS unsigned char* lds) {
;     ...
;         for (int mt = 0; mt < 64; ++mt) {
;             u32x2 unext = ucur; if (mt < 63) unext = *(const u32x2*)(zrow + (size_t)(mt + 1) * 16 * DM);
;             const bf16x4 af = __builtin_bit_cast(bf16x4, ucur);
;             f32x4 d[8];
; #pragma unroll
;             for (int t = 0; t < 8; ++t) d[t] = __builtin_amdgcn_mfma_f32_16x16x16bf16_1k(af, bf[t], (f32x4){0.f, 0.f, 0.f, 0.f}, 0, 0, 0);
; #pragma unroll
;             for (int tq = 0; tq < 4; ++tq)
; #pragma unroll
;                 for (int j = 0; j < 4; ++j) *(LAS f32x2*)(BU + (4 * fq + j) * 528 + (16 * tq + fr) * 8) = (f32x2){d[tq][j], d[tq + 4][j]};
;             asm volatile("s_waitcnt lgkmcnt(0)" ::: "memory");
; #pragma unroll
;             for (int j = 0; j < 16; ++j) {
;                 const f32x2 bu = *(const LAS f32x2*)(BU + j * 528 + lane * 8);
;                 sv = __builtin_elementwise_fma(ayn, __builtin_shufflevector(sv, sv, 1, 0), __builtin_elementwise_fma(axx, sv, bu));
;                 if (PASS == 2) *(LAS unsigned*)(SI + j * 272 + lane * 4) = cvt_pk_bf16(sv.x, sv.y);
;             }
	v_mfma_f32_32x32x16_bf16 v[88:103], v[156:159], v[12:15], 0
	v_mfma_f32_32x32x16_bf16 v[104:119], v[156:159], v[20:23], 0
	v_fma_f32 v70, v30, v34, v124
	v_fma_f32 v71, v30, v35, v230
	v_fma_f32 v72, v10, v35, v70
	v_fma_f32 v73, v11, v34, v71
	v_fma_f32 v70, v30, v72, v125
	v_fma_f32 v71, v30, v73, v231
	v_fma_f32 v34, v10, v73, v70
	v_fma_f32 v35, v11, v72, v71
	v_fma_f32 v70, v30, v34, v126
	v_fma_f32 v71, v30, v35, v232
	v_fma_f32 v72, v10, v35, v70
	v_fma_f32 v73, v11, v34, v71
	v_fma_f32 v70, v30, v72, v127
	v_fma_f32 v71, v30, v73, v233
	v_fma_f32 v34, v10, v73, v70
	v_fma_f32 v35, v11, v72, v71
	v_mfma_f32_32x32x16_bf16 v[88:103], v[200:203], v[16:19], v[88:103]
	v_mfma_f32_32x32x16_bf16 v[104:119], v[200:203], v[24:27], v[104:119]
	v_fma_f32 v70, v30, v34, v128
	v_fma_f32 v71, v30, v35, v234
	v_fma_f32 v72, v10, v35, v70
	v_fma_f32 v73, v11, v34, v71
	v_fma_f32 v70, v30, v72, v129
	v_fma_f32 v71, v30, v73, v235
	v_fma_f32 v34, v10, v73, v70
	v_fma_f32 v35, v11, v72, v71
	v_fma_f32 v70, v30, v34, v130
	v_fma_f32 v71, v30, v35, v236
	v_fma_f32 v72, v10, v35, v70
	v_fma_f32 v73, v11, v34, v71
	v_fma_f32 v70, v30, v72, v131
	v_fma_f32 v71, v30, v73, v237
	v_fma_f32 v34, v10, v73, v70
	v_fma_f32 v35, v11, v72, v71
	v_fma_f32 v70, v30, v34, v132
	v_fma_f32 v71, v30, v35, v238
	v_fma_f32 v72, v10, v35, v70
	v_fma_f32 v73, v11, v34, v71
	v_fma_f32 v70, v30, v72, v133
	v_fma_f32 v71, v30, v73, v239
	v_fma_f32 v34, v10, v73, v70
	v_fma_f32 v35, v11, v72, v71
	v_fma_f32 v70, v30, v34, v134
	v_fma_f32 v71, v30, v35, v240
	v_fma_f32 v72, v10, v35, v70
	v_fma_f32 v73, v11, v34, v71
	v_fma_f32 v70, v30, v72, v135
	v_fma_f32 v71, v30, v73, v241
	v_fma_f32 v34, v10, v73, v70
	v_fma_f32 v35, v11, v72, v71
	s_waitcnt vmcnt(9)
	ds_write_b64 v146, v[52:53]
	ds_read_b128 v[156:159], v196
	ds_read_b128 v[200:203], v197
	global_load_dwordx2 v[46:47], v[54:55], off
	v_lshl_add_u64 v[54:55], v[54:55], 0, s[20:21]
	global_load_dwordx2 v[144:145], v[54:55], off
	v_fma_f32 v70, v30, v34, v88
	v_fma_f32 v71, v30, v35, v104
	v_fma_f32 v72, v10, v35, v70
	v_fma_f32 v73, v11, v34, v71
	v_fma_f32 v70, v30, v72, v89
	v_fma_f32 v71, v30, v73, v105
	v_fma_f32 v34, v10, v73, v70
	v_fma_f32 v35, v11, v72, v71
	v_fma_f32 v70, v30, v34, v90
	v_fma_f32 v71, v30, v35, v106
	v_fma_f32 v72, v10, v35, v70
	v_fma_f32 v73, v11, v34, v71
	v_fma_f32 v70, v30, v72, v91
	v_fma_f32 v71, v30, v73, v107
	v_fma_f32 v34, v10, v73, v70
	v_fma_f32 v35, v11, v72, v71
	s_waitcnt lgkmcnt(0)
	v_mfma_f32_32x32x16_bf16 v[120:135], v[156:159], v[12:15], 0
	v_mfma_f32_32x32x16_bf16 v[226:241], v[156:159], v[20:23], 0
	v_fma_f32 v70, v30, v34, v92
	v_fma_f32 v71, v30, v35, v108
	v_fma_f32 v72, v10, v35, v70
	v_fma_f32 v73, v11, v34, v71
	v_fma_f32 v70, v30, v72, v93
	v_fma_f32 v71, v30, v73, v109
	v_fma_f32 v34, v10, v73, v70
	v_fma_f32 v35, v11, v72, v71
	v_fma_f32 v70, v30, v34, v94
	v_fma_f32 v71, v30, v35, v110
	v_fma_f32 v72, v10, v35, v70
	v_fma_f32 v73, v11, v34, v71
	v_fma_f32 v70, v30, v72, v95
	v_fma_f32 v71, v30, v73, v111
	v_fma_f32 v34, v10, v73, v70
	v_fma_f32 v35, v11, v72, v71
	v_mfma_f32_32x32x16_bf16 v[120:135], v[200:203], v[16:19], v[120:135]
	v_mfma_f32_32x32x16_bf16 v[226:241], v[200:203], v[24:27], v[226:241]
	v_fma_f32 v70, v30, v34, v96
	v_fma_f32 v71, v30, v35, v112
	v_fma_f32 v72, v10, v35, v70
	v_fma_f32 v73, v11, v34, v71
	v_fma_f32 v70, v30, v72, v97
	v_fma_f32 v71, v30, v73, v113
	v_fma_f32 v34, v10, v73, v70
	v_fma_f32 v35, v11, v72, v71
	v_fma_f32 v70, v30, v34, v98
	v_fma_f32 v71, v30, v35, v114
	v_fma_f32 v72, v10, v35, v70
	v_fma_f32 v73, v11, v34, v71
	v_fma_f32 v70, v30, v72, v99
	v_fma_f32 v71, v30, v73, v115
	v_fma_f32 v34, v10, v73, v70
	v_fma_f32 v35, v11, v72, v71
	v_fma_f32 v70, v30, v34, v100
	v_fma_f32 v71, v30, v35, v116
	v_fma_f32 v72, v10, v35, v70
	v_fma_f32 v73, v11, v34, v71
	v_fma_f32 v70, v30, v72, v101
	v_fma_f32 v71, v30, v73, v117
	v_fma_f32 v34, v10, v73, v70
	v_fma_f32 v35, v11, v72, v71
	v_fma_f32 v70, v30, v34, v102
	v_fma_f32 v71, v30, v35, v118
	v_fma_f32 v72, v10, v35, v70
	v_fma_f32 v73, v11, v34, v71
	v_fma_f32 v70, v30, v72, v103
	v_fma_f32 v71, v30, v73, v119
	v_fma_f32 v34, v10, v73, v70
	v_fma_f32 v35, v11, v72, v71
	s_waitcnt vmcnt(9)
	ds_write_b64 v146, v[36:37]
	ds_read_b128 v[156:159], v196
	ds_read_b128 v[200:203], v197
	global_load_dwordx2 v[48:49], v[54:55], off
	v_lshl_add_u64 v[54:55], v[54:55], 0, s[20:21]
	v_cvt_pk_bf16_f32 v82, v60, v61
	v_cvt_pk_bf16_f32 v83, v62, v63
	v_cvt_pk_bf16_f32 v84, v64, v65
	v_cvt_pk_bf16_f32 v85, v66, v67
	global_store_dwordx4 v[58:59], v[82:85], off
	s_mov_b64 s[22:23], 0x200000
	v_lshl_add_u64 v[58:59], v[58:59], 0, s[22:23]
	v_fma_f32 v70, v30, v34, v120
	v_fma_f32 v71, v30, v35, v226
	v_fma_f32 v72, v10, v35, v70
	v_fma_f32 v73, v11, v34, v71
	v_fma_f32 v70, v30, v72, v121
	v_fma_f32 v71, v30, v73, v227
	v_fma_f32 v34, v10, v73, v70
	v_fma_f32 v35, v11, v72, v71
	v_fma_f32 v70, v30, v34, v122
	v_fma_f32 v71, v30, v35, v228
	v_fma_f32 v72, v10, v35, v70
	v_fma_f32 v73, v11, v34, v71
	v_fma_f32 v70, v30, v72, v123
	v_fma_f32 v71, v30, v73, v229
	v_fma_f32 v34, v10, v73, v70
	v_fma_f32 v35, v11, v72, v71
	s_waitcnt lgkmcnt(0)
	v_mfma_f32_32x32x16_bf16 v[88:103], v[156:159], v[12:15], 0
	v_mfma_f32_32x32x16_bf16 v[104:119], v[156:159], v[20:23], 0
	v_fma_f32 v70, v30, v34, v124
	v_fma_f32 v71, v30, v35, v230
	v_fma_f32 v72, v10, v35, v70
	v_fma_f32 v73, v11, v34, v71
	v_fma_f32 v70, v30, v72, v125
	v_fma_f32 v71, v30, v73, v231
	v_fma_f32 v34, v10, v73, v70
	v_fma_f32 v35, v11, v72, v71
	v_fma_f32 v70, v30, v34, v126
	v_fma_f32 v71, v30, v35, v232
	v_fma_f32 v72, v10, v35, v70
	v_fma_f32 v73, v11, v34, v71
	v_fma_f32 v70, v30, v72, v127
	v_fma_f32 v71, v30, v73, v233
	v_fma_f32 v34, v10, v73, v70
	v_fma_f32 v35, v11, v72, v71
	v_mfma_f32_32x32x16_bf16 v[88:103], v[200:203], v[16:19], v[88:103]
	v_mfma_f32_32x32x16_bf16 v[104:119], v[200:203], v[24:27], v[104:119]
	v_fma_f32 v70, v30, v34, v128
	v_fma_f32 v71, v30, v35, v234
	v_fma_f32 v72, v10, v35, v70
	v_fma_f32 v73, v11, v34, v71
	v_fma_f32 v70, v30, v72, v129
	v_fma_f32 v71, v30, v73, v235
	v_fma_f32 v34, v10, v73, v70
	v_fma_f32 v35, v11, v72, v71
	v_fma_f32 v70, v30, v34, v130
	v_fma_f32 v71, v30, v35, v236
	v_fma_f32 v72, v10, v35, v70
	v_fma_f32 v73, v11, v34, v71
	v_fma_f32 v70, v30, v72, v131
	v_fma_f32 v71, v30, v73, v237
	v_fma_f32 v34, v10, v73, v70
	v_fma_f32 v35, v11, v72, v71
	v_fma_f32 v70, v30, v34, v132
	v_fma_f32 v71, v30, v35, v238
	v_fma_f32 v72, v10, v35, v70
	v_fma_f32 v73, v11, v34, v71
	v_fma_f32 v70, v30, v72, v133
	v_fma_f32 v71, v30, v73, v239
	v_fma_f32 v34, v10, v73, v70
	v_fma_f32 v35, v11, v72, v71
	v_fma_f32 v70, v30, v34, v134
	v_fma_f32 v71, v30, v35, v240
	v_fma_f32 v72, v10, v35, v70
	v_fma_f32 v73, v11, v34, v71
	v_fma_f32 v70, v30, v72, v135
	v_fma_f32 v71, v30, v73, v241
	v_fma_f32 v34, v10, v73, v70
	v_fma_f32 v35, v11, v72, v71
	s_add_u32 s12, s12, 8
	s_cmp_eq_u32 s12, 64
	s_cbranch_scc0 .Lp1_loop
; __device__ __forceinline__ unsigned cvt_pk_bf16(float lo, float hi) { const f32x2 v = {lo, hi}; return __builtin_bit_cast(unsigned, __builtin_convertvector(v, bfx2_t)); }
; __device__ __forceinline__ void conv_p(const Params& P, int l) {
;     ...
;         for (int q = 0; q < 4; ++q) { u32x4 w; w.x = cvt_pk_bf16(a[q][0], a[q][1]); w.y = cvt_pk_bf16(a[q][2], a[q][3]); w.z = cvt_pk_bf16(b[q][0], b[q][1]); w.w = cvt_pk_bf16(b[q][2], b[q][3]);
;             *(u32x4*)(dst + (i + q * stride) * 8) = w; }
	s_waitcnt vmcnt(0)
	v_cvt_pk_bf16_f32 v82, v74, v75
	v_cvt_pk_bf16_f32 v83, v76, v77
	v_cvt_pk_bf16_f32 v84, v78, v79
	v_cvt_pk_bf16_f32 v85, v80, v81
	global_store_dwordx4 v[58:59], v[82:85], off
	s_mov_b64 s[22:23], 0x200000
	v_lshl_add_u64 v[58:59], v[58:59], 0, s[22:23]
	s_waitcnt lgkmcnt(0)
	s_branch .LBB0_338
